# K-loops: per-phase s_setprio flips removed, one static s_setprio 1 for waves 4-7 at kernel entry
# baseline (speedup 1.0000x reference)
; #define LAS __attribute__((address_space(3)))
; __global__ void __launch_bounds__(512) fwd_megakernel(Params p) {
;   extern __shared__ __attribute__((aligned(16))) char lds[];
;   volatile LAS unsigned* xst = (volatile LAS unsigned*)(lds + GEMM_LDS);
;   if (threadIdx.x == 0) { xst[0] = 0u; xst[1] = 0u; }
;   __syncthreads();
;   XcdBarrier xb = xcd_barrier_post(g_xbar, xst);
_Z14fwd_megakernel6Params:
	v_readfirstlane_b32 s98, v0
	s_nop 3
	s_cmp_lt_u32 s98, 0x100
	s_cbranch_scc1 .Lprio_done
	s_setprio 1
.Lprio_done:
	s_load_dwordx4 s[4:7], s[0:1], 0xe0
	s_mov_b32 s12, s2
	s_waitcnt lgkmcnt(0)
	v_writelane_b32 v244, s4, 0
	s_nop 1
	v_writelane_b32 v244, s5, 1
	v_writelane_b32 v244, s6, 2
	v_writelane_b32 v244, s7, 3
	s_load_dwordx8 s[4:11], s[0:1], 0xc0
	s_waitcnt lgkmcnt(0)
	v_writelane_b32 v244, s4, 4
	s_nop 1
	v_writelane_b32 v244, s5, 5
	v_writelane_b32 v244, s6, 6
	v_writelane_b32 v244, s7, 7
	v_writelane_b32 v244, s8, 8
	v_writelane_b32 v244, s9, 9
	v_writelane_b32 v244, s10, 10
	v_writelane_b32 v244, s11, 11
	v_cmp_eq_u32_e64 s[4:5], 0, v0
	s_mov_b64 s[2:3], exec
	s_nop 0
	v_writelane_b32 v244, s4, 12
	s_nop 1
	v_writelane_b32 v244, s5, 13
	s_and_b64 s[4:5], s[2:3], s[4:5]
	s_mov_b64 exec, s[4:5]
	s_cbranch_execz .LBB0_2
	s_add_i32 s4, 0, 0x20000
	v_mov_b32_e32 v1, 0
	v_mov_b32_e32 v2, s4
	s_add_i32 s4, 0, 0x20004
	ds_write_b32 v2, v1
	v_mov_b32_e32 v2, s4
	ds_write_b32 v2, v1

; #define PG8_STAGE(bufoff, gbase) do { _Pragma("unroll") for (int _i = 0; _i < 2; ++_i) \
;         __builtin_amdgcn_global_load_lds((const unsigned*)((const char*)(gbase) + voff[_i]), (LAS unsigned*)(lds + (bufoff) + ldsw + _i * 8192), 16, 0, 0); } while (0)
; #define PG8_LDA(dst, b, h) do { _Pragma("unroll") for (int m = 0; m < 4; ++m) _Pragma("unroll") for (int k = 0; k < 2; ++k) dst[m][k] = *(const LAS bf16x8*)(lds + PG8_SA(b, h) + aoff + m * 2048 + k * 1024); } while (0)
; #define PG8_LDB(dst, b, h) do { _Pragma("unroll") for (int n = 0; n < 2; ++n) _Pragma("unroll") for (int k = 0; k < 2; ++k) dst[n][k] = *(const LAS bf16x8*)(lds + PG8_SB(b, h) + boff + n * 2048 + k * 1024); } while (0)
; #define PG8_MMA(ai, bj, At, Bt) do { __builtin_amdgcn_s_setprio(1); _Pragma("unroll") for (int m = 0; m < 4; ++m) _Pragma("unroll") for (int n = 0; n < 2; ++n) _Pragma("unroll") for (int k = 0; k < 2; ++k) \
;         acc[ai][bj][m][n] = __builtin_amdgcn_mfma_f32_16x16x32_bf16(Bt[n][k], At[m][k], acc[ai][bj][m][n], 0, 0, 0); __builtin_amdgcn_s_setprio(0); } while (0)
; #define PG8_WAIT_V(n) asm volatile("s_waitcnt vmcnt(" #n ")" ::: "memory")
; #define PG8_WAIT_L(n) asm volatile("s_waitcnt lgkmcnt(" #n ")" ::: "memory")
; #define PG8_BAR __builtin_amdgcn_s_barrier()
; #define PG8_SCHED __builtin_amdgcn_sched_barrier(0)
; template <int EPI> ...
;     ...
;         for (int t = 0; t < cnk; t += 2) {
;             const bool last = (t == cnk - 2);
;             const char* a1 = cA + (size_t)(t + 1) * kstep;
;             const char* a2 = last ? nA : cA + (size_t)(t + 2) * kstep; const char* b2 = last ? nB : cB + (size_t)(t + 2) * kstep;
;             const char* a3 = a2 + kstep; const char* b3 = b2 + kstep;
;             PG8_LDB(B0, 0, 0); PG8_LDB(B1, 0, 1); PG8_SCHED; PG8_LDA(At, 0, 0); PG8_STAGE(PG8_SA(1, 1), a1 + hstep);
;             PG8_WAIT_V(8); PG8_WAIT_L(0); PG8_BAR; PG8_MMA(0, 0, At, B0); PG8_MMA(0, 1, At, B1); PG8_BAR; PG8_SCHED;
;             PG8_LDA(At, 0, 1); PG8_STAGE(PG8_SB(0, 0), b2); PG8_STAGE(PG8_SB(0, 1), b2 + hstep); PG8_STAGE(PG8_SA(0, 0), a2);
;             PG8_WAIT_V(8); PG8_WAIT_L(0); PG8_BAR; PG8_MMA(1, 0, At, B0); PG8_MMA(1, 1, At, B1); PG8_BAR; PG8_SCHED;
.LBB0_137:
	ds_read_b128 v[130:133], v178
	ds_read_b128 v[164:167], v178 offset:1024
	ds_read_b128 v[168:171], v178 offset:2048
	ds_read_b128 v[172:175], v178 offset:3072
	ds_read_b128 v[188:191], v179
	ds_read_b128 v[192:195], v179 offset:1024
	ds_read_b128 v[196:199], v179 offset:2048
	ds_read_b128 v[200:203], v179 offset:3072
	s_add_u32 s28, s26, 0xfffc0080
	s_addc_u32 s29, s27, -1
	s_cmp_eq_u32 s36, 12
	s_cselect_b32 s31, s5, s29
	s_cselect_b32 s30, s7, s28
	s_cselect_b32 s29, s19, s35
	s_cselect_b32 s28, s21, s34
	v_lshl_add_u64 v[176:177], s[26:27], 0, v[156:157]
	s_add_i32 m0, s42, 0xc000
	ds_read_b128 v[204:207], v180
	ds_read_b128 v[208:211], v180 offset:1024
	ds_read_b128 v[212:215], v180 offset:2048
	ds_read_b128 v[216:219], v180 offset:3072
	ds_read_b128 v[220:223], v180 offset:4096
	ds_read_b128 v[224:227], v180 offset:5120
	ds_read_b128 v[228:231], v180 offset:6144
	ds_read_b128 v[232:235], v180 offset:7168
	global_load_lds_dwordx4 v[176:177], off
	v_lshl_add_u64 v[176:177], s[26:27], 0, v[158:159]
	s_add_i32 m0, s42, 0xe000
	s_nop 0
	global_load_lds_dwordx4 v[176:177], off
	s_waitcnt vmcnt(8)
	s_waitcnt lgkmcnt(0)
	s_barrier
	s_waitcnt lgkmcnt(0)
	v_mfma_f32_16x16x32_bf16 v[126:129], v[130:133], v[204:207], v[126:129]
	v_mfma_f32_16x16x32_bf16 v[122:125], v[168:171], v[204:207], v[122:125]
	v_mfma_f32_16x16x32_bf16 v[118:121], v[130:133], v[212:215], v[118:121]
	v_mfma_f32_16x16x32_bf16 v[114:117], v[168:171], v[212:215], v[114:117]
	v_mfma_f32_16x16x32_bf16 v[110:113], v[130:133], v[220:223], v[110:113]
	v_mfma_f32_16x16x32_bf16 v[106:109], v[168:171], v[220:223], v[106:109]
	v_mfma_f32_16x16x32_bf16 v[102:105], v[130:133], v[228:231], v[102:105]
	v_mfma_f32_16x16x32_bf16 v[98:101], v[168:171], v[228:231], v[98:101]
	v_mfma_f32_16x16x32_bf16 v[126:129], v[164:167], v[208:211], v[126:129]
	v_mfma_f32_16x16x32_bf16 v[122:125], v[172:175], v[208:211], v[122:125]
	v_mfma_f32_16x16x32_bf16 v[118:121], v[164:167], v[216:219], v[118:121]
	v_mfma_f32_16x16x32_bf16 v[114:117], v[172:175], v[216:219], v[114:117]
	v_mfma_f32_16x16x32_bf16 v[110:113], v[164:167], v[224:227], v[110:113]
	v_mfma_f32_16x16x32_bf16 v[106:109], v[172:175], v[224:227], v[106:109]
	v_mfma_f32_16x16x32_bf16 v[102:105], v[164:167], v[232:235], v[102:105]
	v_mfma_f32_16x16x32_bf16 v[98:101], v[172:175], v[232:235], v[98:101]
	v_mfma_f32_16x16x32_bf16 v[62:65], v[188:191], v[204:207], v[62:65]
	v_mfma_f32_16x16x32_bf16 v[58:61], v[196:199], v[204:207], v[58:61]
	v_mfma_f32_16x16x32_bf16 v[54:57], v[188:191], v[212:215], v[54:57]
	v_mfma_f32_16x16x32_bf16 v[50:53], v[196:199], v[212:215], v[50:53]
	v_mfma_f32_16x16x32_bf16 v[46:49], v[188:191], v[220:223], v[46:49]
	v_mfma_f32_16x16x32_bf16 v[42:45], v[196:199], v[220:223], v[42:45]
	v_mfma_f32_16x16x32_bf16 v[38:41], v[188:191], v[228:231], v[38:41]
	v_mfma_f32_16x16x32_bf16 v[34:37], v[196:199], v[228:231], v[34:37]
	v_mfma_f32_16x16x32_bf16 v[62:65], v[192:195], v[208:211], v[62:65]
	v_mfma_f32_16x16x32_bf16 v[58:61], v[200:203], v[208:211], v[58:61]
	v_mfma_f32_16x16x32_bf16 v[54:57], v[192:195], v[216:219], v[54:57]
	v_mfma_f32_16x16x32_bf16 v[50:53], v[200:203], v[216:219], v[50:53]
	v_mfma_f32_16x16x32_bf16 v[46:49], v[192:195], v[224:227], v[46:49]
	v_mfma_f32_16x16x32_bf16 v[42:45], v[200:203], v[224:227], v[42:45]
	v_mfma_f32_16x16x32_bf16 v[38:41], v[192:195], v[232:235], v[38:41]
	v_mfma_f32_16x16x32_bf16 v[34:37], v[200:203], v[232:235], v[34:37]
	s_barrier
	s_add_i32 s37, s55, s41
	v_lshl_add_u64 v[176:177], s[28:29], 0, v[136:137]
	s_mov_b32 m0, s37
	ds_read_b128 v[204:207], v180 offset:16384
	ds_read_b128 v[208:211], v180 offset:17408
	ds_read_b128 v[212:215], v180 offset:18432
	ds_read_b128 v[216:219], v180 offset:19456
	ds_read_b128 v[220:223], v180 offset:20480
	ds_read_b128 v[224:227], v180 offset:21504
	ds_read_b128 v[228:231], v180 offset:22528
	ds_read_b128 v[232:235], v180 offset:23552
	global_load_lds_dwordx4 v[176:177], off
	s_add_i32 m0, s37, 0x2000
	s_add_u32 s38, s28, 0x40000
	v_lshl_add_u64 v[236:237], s[28:29], 0, v[138:139]
	s_addc_u32 s39, s29, 0
	s_add_i32 s37, s56, s41
	global_load_lds_dwordx4 v[236:237], off
	v_lshl_add_u64 v[238:239], s[38:39], 0, v[136:137]
	s_mov_b32 m0, s37
	v_lshl_add_u64 v[240:241], s[30:31], 0, v[138:139]
	global_load_lds_dwordx4 v[238:239], off
	v_lshl_add_u64 v[238:239], s[38:39], 0, v[138:139]
	s_add_i32 m0, s37, 0x2000
	s_nop 0
	global_load_lds_dwordx4 v[238:239], off
	v_lshl_add_u64 v[238:239], s[30:31], 0, v[136:137]
	s_mov_b32 m0, s42
	s_nop 0
	global_load_lds_dwordx4 v[238:239], off
	s_mov_b32 m0, s43
	s_nop 0
	global_load_lds_dwordx4 v[240:241], off
	s_waitcnt vmcnt(8)
	s_waitcnt lgkmcnt(0)
	s_barrier
; #define PG8_STAGE(bufoff, gbase) do { _Pragma("unroll") for (int _i = 0; _i < 2; ++_i) \
;         __builtin_amdgcn_global_load_lds((const unsigned*)((const char*)(gbase) + voff[_i]), (LAS unsigned*)(lds + (bufoff) + ldsw + _i * 8192), 16, 0, 0); } while (0)
; #define PG8_LDA(dst, b, h) do { _Pragma("unroll") for (int m = 0; m < 4; ++m) _Pragma("unroll") for (int k = 0; k < 2; ++k) dst[m][k] = *(const LAS bf16x8*)(lds + PG8_SA(b, h) + aoff + m * 2048 + k * 1024); } while (0)
; #define PG8_LDB(dst, b, h) do { _Pragma("unroll") for (int n = 0; n < 2; ++n) _Pragma("unroll") for (int k = 0; k < 2; ++k) dst[n][k] = *(const LAS bf16x8*)(lds + PG8_SB(b, h) + boff + n * 2048 + k * 1024); } while (0)
; #define PG8_MMA(ai, bj, At, Bt) do { __builtin_amdgcn_s_setprio(1); _Pragma("unroll") for (int m = 0; m < 4; ++m) _Pragma("unroll") for (int n = 0; n < 2; ++n) _Pragma("unroll") for (int k = 0; k < 2; ++k) \
;         acc[ai][bj][m][n] = __builtin_amdgcn_mfma_f32_16x16x32_bf16(Bt[n][k], At[m][k], acc[ai][bj][m][n], 0, 0, 0); __builtin_amdgcn_s_setprio(0); } while (0)
; #define PG8_WAIT_V(n) asm volatile("s_waitcnt vmcnt(" #n ")" ::: "memory")
; #define PG8_WAIT_L(n) asm volatile("s_waitcnt lgkmcnt(" #n ")" ::: "memory")
; #define PG8_BAR __builtin_amdgcn_s_barrier()
; #define PG8_SCHED __builtin_amdgcn_sched_barrier(0)
; template <int EPI> ...
;     ...
;             PG8_LDA(At, 0, 1); PG8_STAGE(PG8_SB(0, 0), b2); PG8_STAGE(PG8_SB(0, 1), b2 + hstep); PG8_STAGE(PG8_SA(0, 0), a2);
;             PG8_WAIT_V(8); PG8_WAIT_L(0); PG8_BAR; PG8_MMA(1, 0, At, B0); PG8_MMA(1, 1, At, B1); PG8_BAR; PG8_SCHED;
;             PG8_LDB(B0, 1, 0); PG8_LDB(B1, 1, 1); PG8_SCHED; PG8_LDA(At, 1, 0); PG8_STAGE(PG8_SA(0, 1), a2 + hstep);
;             PG8_WAIT_V(8); PG8_WAIT_L(0); PG8_BAR; PG8_MMA(0, 0, At, B0); PG8_MMA(0, 1, At, B1); PG8_BAR; PG8_SCHED;
	s_waitcnt lgkmcnt(0)
	v_mfma_f32_16x16x32_bf16 v[94:97], v[130:133], v[204:207], v[94:97]
	v_mfma_f32_16x16x32_bf16 v[90:93], v[168:171], v[204:207], v[90:93]
	v_mfma_f32_16x16x32_bf16 v[86:89], v[130:133], v[212:215], v[86:89]
	v_mfma_f32_16x16x32_bf16 v[82:85], v[168:171], v[212:215], v[82:85]
	v_mfma_f32_16x16x32_bf16 v[78:81], v[130:133], v[220:223], v[78:81]
	v_mfma_f32_16x16x32_bf16 v[74:77], v[168:171], v[220:223], v[74:77]
	v_mfma_f32_16x16x32_bf16 v[70:73], v[130:133], v[228:231], v[70:73]
	v_mfma_f32_16x16x32_bf16 v[66:69], v[168:171], v[228:231], v[66:69]
	v_mfma_f32_16x16x32_bf16 v[94:97], v[164:167], v[208:211], v[94:97]
	v_mfma_f32_16x16x32_bf16 v[90:93], v[172:175], v[208:211], v[90:93]
	v_mfma_f32_16x16x32_bf16 v[86:89], v[164:167], v[216:219], v[86:89]
	v_mfma_f32_16x16x32_bf16 v[82:85], v[172:175], v[216:219], v[82:85]
	v_mfma_f32_16x16x32_bf16 v[78:81], v[164:167], v[224:227], v[78:81]
	v_mfma_f32_16x16x32_bf16 v[74:77], v[172:175], v[224:227], v[74:77]
	v_mfma_f32_16x16x32_bf16 v[70:73], v[164:167], v[232:235], v[70:73]
	v_mfma_f32_16x16x32_bf16 v[66:69], v[172:175], v[232:235], v[66:69]
	v_mfma_f32_16x16x32_bf16 v[30:33], v[188:191], v[204:207], v[30:33]
	v_mfma_f32_16x16x32_bf16 v[26:29], v[196:199], v[204:207], v[26:29]
	v_mfma_f32_16x16x32_bf16 v[22:25], v[188:191], v[212:215], v[22:25]
	v_mfma_f32_16x16x32_bf16 v[18:21], v[196:199], v[212:215], v[18:21]
	v_mfma_f32_16x16x32_bf16 v[14:17], v[188:191], v[220:223], v[14:17]
	v_mfma_f32_16x16x32_bf16 v[10:13], v[196:199], v[220:223], v[10:13]
	v_mfma_f32_16x16x32_bf16 v[6:9], v[188:191], v[228:231], v[6:9]
	v_mfma_f32_16x16x32_bf16 v[2:5], v[196:199], v[228:231], v[2:5]
	v_mfma_f32_16x16x32_bf16 v[30:33], v[192:195], v[208:211], v[30:33]
	v_mfma_f32_16x16x32_bf16 v[26:29], v[200:203], v[208:211], v[26:29]
	v_mfma_f32_16x16x32_bf16 v[22:25], v[192:195], v[216:219], v[22:25]
	v_mfma_f32_16x16x32_bf16 v[18:21], v[200:203], v[216:219], v[18:21]
	v_mfma_f32_16x16x32_bf16 v[14:17], v[192:195], v[224:227], v[14:17]
	v_mfma_f32_16x16x32_bf16 v[10:13], v[200:203], v[224:227], v[10:13]
	v_mfma_f32_16x16x32_bf16 v[6:9], v[192:195], v[232:235], v[6:9]
	v_mfma_f32_16x16x32_bf16 v[2:5], v[200:203], v[232:235], v[2:5]
	s_barrier
	s_add_i32 s37, 0, 0x18000
	v_add_u32_e32 v140, s37, v147
	s_add_i32 s38, 0, 0x1c000
	ds_read_b128 v[130:133], v140
	ds_read_b128 v[164:167], v140 offset:1024
	ds_read_b128 v[168:171], v140 offset:2048
	ds_read_b128 v[172:175], v140 offset:3072
	v_add_u32_e32 v140, s38, v147
	ds_read_b128 v[188:191], v140
	ds_read_b128 v[192:195], v140 offset:1024
	ds_read_b128 v[196:199], v140 offset:2048
	ds_read_b128 v[200:203], v140 offset:3072
	s_add_u32 s30, s30, 0x40000
	s_addc_u32 s31, s31, 0
	s_mov_b32 m0, s44
	v_lshl_add_u64 v[242:243], s[30:31], 0, v[136:137]
	ds_read_b128 v[204:207], v180 offset:32768
	ds_read_b128 v[208:211], v180 offset:33792
	ds_read_b128 v[212:215], v180 offset:34816
	ds_read_b128 v[216:219], v180 offset:35840
	ds_read_b128 v[220:223], v180 offset:36864
	ds_read_b128 v[224:227], v180 offset:37888
	ds_read_b128 v[228:231], v180 offset:38912
	ds_read_b128 v[232:235], v180 offset:39936
	global_load_lds_dwordx4 v[242:243], off
	v_lshl_add_u64 v[242:243], s[30:31], 0, v[138:139]
	s_mov_b32 m0, s45
	s_nop 0
	global_load_lds_dwordx4 v[242:243], off
	s_waitcnt vmcnt(8)
	s_waitcnt lgkmcnt(0)
	s_barrier
	s_waitcnt lgkmcnt(0)
	v_mfma_f32_16x16x32_bf16 v[126:129], v[130:133], v[204:207], v[126:129]
	v_mfma_f32_16x16x32_bf16 v[122:125], v[168:171], v[204:207], v[122:125]
	v_mfma_f32_16x16x32_bf16 v[118:121], v[130:133], v[212:215], v[118:121]
	v_mfma_f32_16x16x32_bf16 v[114:117], v[168:171], v[212:215], v[114:117]
	v_mfma_f32_16x16x32_bf16 v[110:113], v[130:133], v[220:223], v[110:113]
	v_mfma_f32_16x16x32_bf16 v[106:109], v[168:171], v[220:223], v[106:109]
	v_mfma_f32_16x16x32_bf16 v[102:105], v[130:133], v[228:231], v[102:105]
	v_mfma_f32_16x16x32_bf16 v[98:101], v[168:171], v[228:231], v[98:101]
	v_mfma_f32_16x16x32_bf16 v[126:129], v[164:167], v[208:211], v[126:129]
	v_mfma_f32_16x16x32_bf16 v[122:125], v[172:175], v[208:211], v[122:125]
	v_mfma_f32_16x16x32_bf16 v[118:121], v[164:167], v[216:219], v[118:121]
	v_mfma_f32_16x16x32_bf16 v[114:117], v[172:175], v[216:219], v[114:117]
	v_mfma_f32_16x16x32_bf16 v[110:113], v[164:167], v[224:227], v[110:113]
	v_mfma_f32_16x16x32_bf16 v[106:109], v[172:175], v[224:227], v[106:109]
	v_mfma_f32_16x16x32_bf16 v[102:105], v[164:167], v[232:235], v[102:105]
	v_mfma_f32_16x16x32_bf16 v[98:101], v[172:175], v[232:235], v[98:101]
	v_mfma_f32_16x16x32_bf16 v[62:65], v[188:191], v[204:207], v[62:65]
	v_mfma_f32_16x16x32_bf16 v[58:61], v[196:199], v[204:207], v[58:61]
	v_mfma_f32_16x16x32_bf16 v[54:57], v[188:191], v[212:215], v[54:57]
	v_mfma_f32_16x16x32_bf16 v[50:53], v[196:199], v[212:215], v[50:53]
	v_mfma_f32_16x16x32_bf16 v[46:49], v[188:191], v[220:223], v[46:49]
	v_mfma_f32_16x16x32_bf16 v[42:45], v[196:199], v[220:223], v[42:45]
	v_mfma_f32_16x16x32_bf16 v[38:41], v[188:191], v[228:231], v[38:41]
	v_mfma_f32_16x16x32_bf16 v[34:37], v[196:199], v[228:231], v[34:37]
	v_mfma_f32_16x16x32_bf16 v[62:65], v[192:195], v[208:211], v[62:65]
	v_mfma_f32_16x16x32_bf16 v[58:61], v[200:203], v[208:211], v[58:61]
	v_mfma_f32_16x16x32_bf16 v[54:57], v[192:195], v[216:219], v[54:57]
	v_mfma_f32_16x16x32_bf16 v[50:53], v[200:203], v[216:219], v[50:53]
	v_mfma_f32_16x16x32_bf16 v[46:49], v[192:195], v[224:227], v[46:49]
	v_mfma_f32_16x16x32_bf16 v[42:45], v[200:203], v[224:227], v[42:45]
	v_mfma_f32_16x16x32_bf16 v[38:41], v[192:195], v[232:235], v[38:41]
	v_mfma_f32_16x16x32_bf16 v[34:37], v[200:203], v[232:235], v[34:37]
	s_barrier
; #define PG8_STAGE(bufoff, gbase) do { _Pragma("unroll") for (int _i = 0; _i < 2; ++_i) \
;         __builtin_amdgcn_global_load_lds((const unsigned*)((const char*)(gbase) + voff[_i]), (LAS unsigned*)(lds + (bufoff) + ldsw + _i * 8192), 16, 0, 0); } while (0)
; #define PG8_LDA(dst, b, h) do { _Pragma("unroll") for (int m = 0; m < 4; ++m) _Pragma("unroll") for (int k = 0; k < 2; ++k) dst[m][k] = *(const LAS bf16x8*)(lds + PG8_SA(b, h) + aoff + m * 2048 + k * 1024); } while (0)
; #define PG8_LDB(dst, b, h) do { _Pragma("unroll") for (int n = 0; n < 2; ++n) _Pragma("unroll") for (int k = 0; k < 2; ++k) dst[n][k] = *(const LAS bf16x8*)(lds + PG8_SB(b, h) + boff + n * 2048 + k * 1024); } while (0)
; #define PG8_MMA(ai, bj, At, Bt) do { __builtin_amdgcn_s_setprio(1); _Pragma("unroll") for (int m = 0; m < 4; ++m) _Pragma("unroll") for (int n = 0; n < 2; ++n) _Pragma("unroll") for (int k = 0; k < 2; ++k) \
;         acc[ai][bj][m][n] = __builtin_amdgcn_mfma_f32_16x16x32_bf16(Bt[n][k], At[m][k], acc[ai][bj][m][n], 0, 0, 0); __builtin_amdgcn_s_setprio(0); } while (0)
; #define PG8_WAIT_V(n) asm volatile("s_waitcnt vmcnt(" #n ")" ::: "memory")
; #define PG8_WAIT_L(n) asm volatile("s_waitcnt lgkmcnt(" #n ")" ::: "memory")
; #define PG8_BAR __builtin_amdgcn_s_barrier()
; #define PG8_SCHED __builtin_amdgcn_sched_barrier(0)
; template <int EPI> ...
;     ...
;             PG8_LDB(B0, 1, 0); PG8_LDB(B1, 1, 1); PG8_SCHED; PG8_LDA(At, 1, 0); PG8_STAGE(PG8_SA(0, 1), a2 + hstep);
;             PG8_WAIT_V(8); PG8_WAIT_L(0); PG8_BAR; PG8_MMA(0, 0, At, B0); PG8_MMA(0, 1, At, B1); PG8_BAR; PG8_SCHED;
;             PG8_LDA(At, 1, 1); PG8_STAGE(PG8_SB(1, 0), b3); PG8_STAGE(PG8_SB(1, 1), b3 + hstep); PG8_STAGE(PG8_SA(1, 0), a3);
;             PG8_WAIT_V(8); PG8_WAIT_L(0); PG8_BAR; PG8_MMA(1, 0, At, B0); PG8_MMA(1, 1, At, B1); PG8_BAR; PG8_SCHED;
;         }
	s_add_i32 s30, s37, s41
	v_lshl_add_u64 v[176:177], v[176:177], 0, s[10:11]
	s_mov_b32 m0, s30
	ds_read_b128 v[204:207], v180 offset:49152
	ds_read_b128 v[208:211], v180 offset:50176
	ds_read_b128 v[212:215], v180 offset:51200
	ds_read_b128 v[216:219], v180 offset:52224
	ds_read_b128 v[220:223], v180 offset:53248
	ds_read_b128 v[224:227], v180 offset:54272
	ds_read_b128 v[228:231], v180 offset:55296
	ds_read_b128 v[232:235], v180 offset:56320
	global_load_lds_dwordx4 v[176:177], off
	s_add_i32 m0, s30, 0x2000
	s_add_u32 s28, s28, 0x40080
	v_lshl_add_u64 v[176:177], v[236:237], 0, s[10:11]
	s_addc_u32 s29, s29, 0
	s_add_i32 s30, s38, s41
	global_load_lds_dwordx4 v[176:177], off
	v_lshl_add_u64 v[176:177], s[28:29], 0, v[136:137]
	s_mov_b32 m0, s30
	s_nop 0
	global_load_lds_dwordx4 v[176:177], off
	v_lshl_add_u64 v[176:177], s[28:29], 0, v[138:139]
	s_add_i32 m0, s30, 0x2000
	s_nop 0
	global_load_lds_dwordx4 v[176:177], off
	v_lshl_add_u64 v[176:177], v[238:239], 0, s[10:11]
	s_mov_b32 m0, s48
	s_nop 0
	global_load_lds_dwordx4 v[176:177], off
	v_lshl_add_u64 v[176:177], v[240:241], 0, s[10:11]
	s_mov_b32 m0, s49
	s_nop 0
	global_load_lds_dwordx4 v[176:177], off
	s_waitcnt vmcnt(8)
	s_waitcnt lgkmcnt(0)
	s_barrier
	s_waitcnt lgkmcnt(0)
	v_mfma_f32_16x16x32_bf16 v[94:97], v[130:133], v[204:207], v[94:97]
	v_mfma_f32_16x16x32_bf16 v[90:93], v[168:171], v[204:207], v[90:93]
	v_mfma_f32_16x16x32_bf16 v[86:89], v[130:133], v[212:215], v[86:89]
	v_mfma_f32_16x16x32_bf16 v[82:85], v[168:171], v[212:215], v[82:85]
	v_mfma_f32_16x16x32_bf16 v[78:81], v[130:133], v[220:223], v[78:81]
	v_mfma_f32_16x16x32_bf16 v[74:77], v[168:171], v[220:223], v[74:77]
	v_mfma_f32_16x16x32_bf16 v[70:73], v[130:133], v[228:231], v[70:73]
	v_mfma_f32_16x16x32_bf16 v[66:69], v[168:171], v[228:231], v[66:69]
	v_mfma_f32_16x16x32_bf16 v[94:97], v[164:167], v[208:211], v[94:97]
	v_mfma_f32_16x16x32_bf16 v[90:93], v[172:175], v[208:211], v[90:93]
	v_mfma_f32_16x16x32_bf16 v[86:89], v[164:167], v[216:219], v[86:89]
	v_mfma_f32_16x16x32_bf16 v[82:85], v[172:175], v[216:219], v[82:85]
	v_mfma_f32_16x16x32_bf16 v[78:81], v[164:167], v[224:227], v[78:81]
	v_mfma_f32_16x16x32_bf16 v[74:77], v[172:175], v[224:227], v[74:77]
	v_mfma_f32_16x16x32_bf16 v[70:73], v[164:167], v[232:235], v[70:73]
	v_mfma_f32_16x16x32_bf16 v[66:69], v[172:175], v[232:235], v[66:69]
	v_mfma_f32_16x16x32_bf16 v[30:33], v[188:191], v[204:207], v[30:33]
	v_mfma_f32_16x16x32_bf16 v[26:29], v[196:199], v[204:207], v[26:29]
	v_mfma_f32_16x16x32_bf16 v[22:25], v[188:191], v[212:215], v[22:25]
	v_mfma_f32_16x16x32_bf16 v[18:21], v[196:199], v[212:215], v[18:21]
	v_mfma_f32_16x16x32_bf16 v[14:17], v[188:191], v[220:223], v[14:17]
	v_mfma_f32_16x16x32_bf16 v[10:13], v[196:199], v[220:223], v[10:13]
	v_mfma_f32_16x16x32_bf16 v[6:9], v[188:191], v[228:231], v[6:9]
	v_mfma_f32_16x16x32_bf16 v[2:5], v[196:199], v[228:231], v[2:5]
	v_mfma_f32_16x16x32_bf16 v[30:33], v[192:195], v[208:211], v[30:33]
	v_mfma_f32_16x16x32_bf16 v[26:29], v[200:203], v[208:211], v[26:29]
	v_mfma_f32_16x16x32_bf16 v[22:25], v[192:195], v[216:219], v[22:25]
	v_mfma_f32_16x16x32_bf16 v[18:21], v[200:203], v[216:219], v[18:21]
	v_mfma_f32_16x16x32_bf16 v[14:17], v[192:195], v[224:227], v[14:17]
	v_mfma_f32_16x16x32_bf16 v[10:13], v[200:203], v[224:227], v[10:13]
	v_mfma_f32_16x16x32_bf16 v[6:9], v[192:195], v[232:235], v[6:9]
	v_mfma_f32_16x16x32_bf16 v[2:5], v[200:203], v[232:235], v[2:5]
	s_barrier
	s_add_i32 s36, s36, 2
	s_add_u32 s26, s26, 0x100
	s_addc_u32 s27, s27, 0
	s_add_u32 s34, s34, 0x100
	s_addc_u32 s35, s35, 0
	s_cmp_gt_u32 s36, 13
	s_cbranch_scc0 .LBB0_137
	s_and_b64 vcc, exec, s[12:13]
	s_cbranch_vccz .LBB0_140
	s_barrier

; #define PG8_STAGE(bufoff, gbase) do { _Pragma("unroll") for (int _i = 0; _i < 2; ++_i) \
;         __builtin_amdgcn_global_load_lds((const unsigned*)((const char*)(gbase) + voff[_i]), (LAS unsigned*)(lds + (bufoff) + ldsw + _i * 8192), 16, 0, 0); } while (0)
; #define PG8_LDA(dst, b, h) do { _Pragma("unroll") for (int m = 0; m < 4; ++m) _Pragma("unroll") for (int k = 0; k < 2; ++k) dst[m][k] = *(const LAS bf16x8*)(lds + PG8_SA(b, h) + aoff + m * 2048 + k * 1024); } while (0)
; #define PG8_LDB(dst, b, h) do { _Pragma("unroll") for (int n = 0; n < 2; ++n) _Pragma("unroll") for (int k = 0; k < 2; ++k) dst[n][k] = *(const LAS bf16x8*)(lds + PG8_SB(b, h) + boff + n * 2048 + k * 1024); } while (0)
; #define PG8_MMA(ai, bj, At, Bt) do { __builtin_amdgcn_s_setprio(1); _Pragma("unroll") for (int m = 0; m < 4; ++m) _Pragma("unroll") for (int n = 0; n < 2; ++n) _Pragma("unroll") for (int k = 0; k < 2; ++k) \
;         acc[ai][bj][m][n] = __builtin_amdgcn_mfma_f32_16x16x32_bf16(Bt[n][k], At[m][k], acc[ai][bj][m][n], 0, 0, 0); __builtin_amdgcn_s_setprio(0); } while (0)
; #define PG8_WAIT_V(n) asm volatile("s_waitcnt vmcnt(" #n ")" ::: "memory")
; #define PG8_WAIT_L(n) asm volatile("s_waitcnt lgkmcnt(" #n ")" ::: "memory")
; #define PG8_BAR __builtin_amdgcn_s_barrier()
; #define PG8_SCHED __builtin_amdgcn_sched_barrier(0)
; template <int EPI> ...
;     ...
;         for (int t = 0; t < cnk; t += 2) {
;             const bool last = (t == cnk - 2);
;             const char* a1 = cA + (size_t)(t + 1) * kstep;
;             const char* a2 = last ? nA : cA + (size_t)(t + 2) * kstep; const char* b2 = last ? nB : cB + (size_t)(t + 2) * kstep;
;             const char* a3 = a2 + kstep; const char* b3 = b2 + kstep;
;             PG8_LDB(B0, 0, 0); PG8_LDB(B1, 0, 1); PG8_SCHED; PG8_LDA(At, 0, 0); PG8_STAGE(PG8_SA(1, 1), a1 + hstep);
;             PG8_WAIT_V(8); PG8_WAIT_L(0); PG8_BAR; PG8_MMA(0, 0, At, B0); PG8_MMA(0, 1, At, B1); PG8_BAR; PG8_SCHED;
;             PG8_LDA(At, 0, 1); PG8_STAGE(PG8_SB(0, 0), b2); PG8_STAGE(PG8_SB(0, 1), b2 + hstep); PG8_STAGE(PG8_SA(0, 0), a2);
;             PG8_WAIT_V(8); PG8_WAIT_L(0); PG8_BAR; PG8_MMA(1, 0, At, B0); PG8_MMA(1, 1, At, B1); PG8_BAR; PG8_SCHED;
.LBB0_656:
	ds_read_b128 v[142:145], v158
	ds_read_b128 v[146:149], v158 offset:1024
	ds_read_b128 v[162:165], v158 offset:2048
	ds_read_b128 v[166:169], v158 offset:3072
	ds_read_b128 v[170:173], v159
	ds_read_b128 v[174:177], v159 offset:1024
	ds_read_b128 v[178:181], v159 offset:2048
	ds_read_b128 v[188:191], v159 offset:3072
	s_add_i32 s63, s62, 2
	s_add_u32 s28, s26, 0xfffe0080
	s_addc_u32 s29, s27, -1
	s_cmp_eq_u32 s59, s62
	s_cselect_b32 s31, s5, s29
	s_cselect_b32 s30, s19, s28
	s_cselect_b32 s29, s17, s61
	s_cselect_b32 s28, s58, s60
	v_lshl_add_u64 v[224:225], s[26:27], 0, v[136:137]
	s_add_i32 m0, s7, 0xc000
	ds_read_b128 v[192:195], v160
	ds_read_b128 v[196:199], v160 offset:1024
	ds_read_b128 v[200:203], v160 offset:2048
	ds_read_b128 v[204:207], v160 offset:3072
	ds_read_b128 v[208:211], v160 offset:4096
	ds_read_b128 v[212:215], v160 offset:5120
	ds_read_b128 v[216:219], v160 offset:6144
	ds_read_b128 v[220:223], v160 offset:7168
	global_load_lds_dwordx4 v[224:225], off
	v_lshl_add_u64 v[224:225], s[26:27], 0, v[138:139]
	s_add_i32 m0, s7, 0xe000
	s_nop 0
	global_load_lds_dwordx4 v[224:225], off
	s_waitcnt vmcnt(8)
	s_waitcnt lgkmcnt(0)
	s_barrier
	s_waitcnt lgkmcnt(0)
	v_mfma_f32_16x16x32_bf16 v[126:129], v[142:145], v[192:195], v[126:129]
	v_mfma_f32_16x16x32_bf16 v[122:125], v[162:165], v[192:195], v[122:125]
	v_mfma_f32_16x16x32_bf16 v[118:121], v[142:145], v[200:203], v[118:121]
	v_mfma_f32_16x16x32_bf16 v[114:117], v[162:165], v[200:203], v[114:117]
	v_mfma_f32_16x16x32_bf16 v[106:109], v[142:145], v[208:211], v[106:109]
	v_mfma_f32_16x16x32_bf16 v[98:101], v[162:165], v[208:211], v[98:101]
	v_mfma_f32_16x16x32_bf16 v[90:93], v[142:145], v[216:219], v[90:93]
	v_mfma_f32_16x16x32_bf16 v[82:85], v[162:165], v[216:219], v[82:85]
	v_mfma_f32_16x16x32_bf16 v[126:129], v[146:149], v[196:199], v[126:129]
	v_mfma_f32_16x16x32_bf16 v[122:125], v[166:169], v[196:199], v[122:125]
	v_mfma_f32_16x16x32_bf16 v[118:121], v[146:149], v[204:207], v[118:121]
	v_mfma_f32_16x16x32_bf16 v[114:117], v[166:169], v[204:207], v[114:117]
	v_mfma_f32_16x16x32_bf16 v[106:109], v[146:149], v[212:215], v[106:109]
	v_mfma_f32_16x16x32_bf16 v[98:101], v[166:169], v[212:215], v[98:101]
	v_mfma_f32_16x16x32_bf16 v[90:93], v[146:149], v[220:223], v[90:93]
	v_mfma_f32_16x16x32_bf16 v[82:85], v[166:169], v[220:223], v[82:85]
	v_mfma_f32_16x16x32_bf16 v[110:113], v[170:173], v[192:195], v[110:113]
	v_mfma_f32_16x16x32_bf16 v[102:105], v[178:181], v[192:195], v[102:105]
	v_mfma_f32_16x16x32_bf16 v[94:97], v[170:173], v[200:203], v[94:97]
	v_mfma_f32_16x16x32_bf16 v[86:89], v[178:181], v[200:203], v[86:89]
	v_mfma_f32_16x16x32_bf16 v[78:81], v[170:173], v[208:211], v[78:81]
	v_mfma_f32_16x16x32_bf16 v[74:77], v[178:181], v[208:211], v[74:77]
	v_mfma_f32_16x16x32_bf16 v[70:73], v[170:173], v[216:219], v[70:73]
	v_mfma_f32_16x16x32_bf16 v[66:69], v[178:181], v[216:219], v[66:69]
	v_mfma_f32_16x16x32_bf16 v[110:113], v[174:177], v[196:199], v[110:113]
	v_mfma_f32_16x16x32_bf16 v[102:105], v[188:191], v[196:199], v[102:105]
	v_mfma_f32_16x16x32_bf16 v[94:97], v[174:177], v[204:207], v[94:97]
	v_mfma_f32_16x16x32_bf16 v[86:89], v[188:191], v[204:207], v[86:89]
	v_mfma_f32_16x16x32_bf16 v[78:81], v[174:177], v[212:215], v[78:81]
	v_mfma_f32_16x16x32_bf16 v[74:77], v[188:191], v[212:215], v[74:77]
	v_mfma_f32_16x16x32_bf16 v[70:73], v[174:177], v[220:223], v[70:73]
	v_mfma_f32_16x16x32_bf16 v[66:69], v[188:191], v[220:223], v[66:69]
	s_barrier
	s_add_i32 s62, s48, s40
	v_lshl_add_u64 v[224:225], s[28:29], 0, v[130:131]
	s_mov_b32 m0, s62
	ds_read_b128 v[192:195], v160 offset:16384
	ds_read_b128 v[196:199], v160 offset:17408
	ds_read_b128 v[200:203], v160 offset:18432
	ds_read_b128 v[204:207], v160 offset:19456
	ds_read_b128 v[208:211], v160 offset:20480
	ds_read_b128 v[212:215], v160 offset:21504
	ds_read_b128 v[216:219], v160 offset:22528
	ds_read_b128 v[220:223], v160 offset:23552
	global_load_lds_dwordx4 v[224:225], off
	s_add_i32 m0, s62, 0x2000
	s_add_u32 s64, s28, 0x20000
	v_lshl_add_u64 v[226:227], s[28:29], 0, v[132:133]
	s_addc_u32 s65, s29, 0
	s_add_i32 s62, s49, s40
	global_load_lds_dwordx4 v[226:227], off
	v_lshl_add_u64 v[228:229], s[64:65], 0, v[130:131]
	s_mov_b32 m0, s62
	v_lshl_add_u64 v[230:231], s[30:31], 0, v[132:133]
	global_load_lds_dwordx4 v[228:229], off
	v_lshl_add_u64 v[228:229], s[64:65], 0, v[132:133]
	s_add_i32 m0, s62, 0x2000
	s_nop 0
	global_load_lds_dwordx4 v[228:229], off
	v_lshl_add_u64 v[228:229], s[30:31], 0, v[130:131]
	s_mov_b32 m0, s7
	s_nop 0
	global_load_lds_dwordx4 v[228:229], off
	s_mov_b32 m0, s42
	s_nop 0
	global_load_lds_dwordx4 v[230:231], off
	s_waitcnt vmcnt(8)
	s_waitcnt lgkmcnt(0)
	s_barrier
; #define PG8_STAGE(bufoff, gbase) do { _Pragma("unroll") for (int _i = 0; _i < 2; ++_i) \
;         __builtin_amdgcn_global_load_lds((const unsigned*)((const char*)(gbase) + voff[_i]), (LAS unsigned*)(lds + (bufoff) + ldsw + _i * 8192), 16, 0, 0); } while (0)
; #define PG8_LDA(dst, b, h) do { _Pragma("unroll") for (int m = 0; m < 4; ++m) _Pragma("unroll") for (int k = 0; k < 2; ++k) dst[m][k] = *(const LAS bf16x8*)(lds + PG8_SA(b, h) + aoff + m * 2048 + k * 1024); } while (0)
; #define PG8_LDB(dst, b, h) do { _Pragma("unroll") for (int n = 0; n < 2; ++n) _Pragma("unroll") for (int k = 0; k < 2; ++k) dst[n][k] = *(const LAS bf16x8*)(lds + PG8_SB(b, h) + boff + n * 2048 + k * 1024); } while (0)
; #define PG8_MMA(ai, bj, At, Bt) do { __builtin_amdgcn_s_setprio(1); _Pragma("unroll") for (int m = 0; m < 4; ++m) _Pragma("unroll") for (int n = 0; n < 2; ++n) _Pragma("unroll") for (int k = 0; k < 2; ++k) \
;         acc[ai][bj][m][n] = __builtin_amdgcn_mfma_f32_16x16x32_bf16(Bt[n][k], At[m][k], acc[ai][bj][m][n], 0, 0, 0); __builtin_amdgcn_s_setprio(0); } while (0)
; #define PG8_WAIT_V(n) asm volatile("s_waitcnt vmcnt(" #n ")" ::: "memory")
; #define PG8_WAIT_L(n) asm volatile("s_waitcnt lgkmcnt(" #n ")" ::: "memory")
; #define PG8_BAR __builtin_amdgcn_s_barrier()
; #define PG8_SCHED __builtin_amdgcn_sched_barrier(0)
; template <int EPI> ...
;     ...
;             PG8_LDA(At, 0, 1); PG8_STAGE(PG8_SB(0, 0), b2); PG8_STAGE(PG8_SB(0, 1), b2 + hstep); PG8_STAGE(PG8_SA(0, 0), a2);
;             PG8_WAIT_V(8); PG8_WAIT_L(0); PG8_BAR; PG8_MMA(1, 0, At, B0); PG8_MMA(1, 1, At, B1); PG8_BAR; PG8_SCHED;
;             PG8_LDB(B0, 1, 0); PG8_LDB(B1, 1, 1); PG8_SCHED; PG8_LDA(At, 1, 0); PG8_STAGE(PG8_SA(0, 1), a2 + hstep);
;             PG8_WAIT_V(8); PG8_WAIT_L(0); PG8_BAR; PG8_MMA(0, 0, At, B0); PG8_MMA(0, 1, At, B1); PG8_BAR; PG8_SCHED;
	s_waitcnt lgkmcnt(0)
	v_mfma_f32_16x16x32_bf16 v[62:65], v[142:145], v[192:195], v[62:65]
	v_mfma_f32_16x16x32_bf16 v[58:61], v[162:165], v[192:195], v[58:61]
	v_mfma_f32_16x16x32_bf16 v[54:57], v[142:145], v[200:203], v[54:57]
	v_mfma_f32_16x16x32_bf16 v[50:53], v[162:165], v[200:203], v[50:53]
	v_mfma_f32_16x16x32_bf16 v[42:45], v[142:145], v[208:211], v[42:45]
	v_mfma_f32_16x16x32_bf16 v[34:37], v[162:165], v[208:211], v[34:37]
	v_mfma_f32_16x16x32_bf16 v[26:29], v[142:145], v[216:219], v[26:29]
	v_mfma_f32_16x16x32_bf16 v[18:21], v[162:165], v[216:219], v[18:21]
	v_mfma_f32_16x16x32_bf16 v[62:65], v[146:149], v[196:199], v[62:65]
	v_mfma_f32_16x16x32_bf16 v[58:61], v[166:169], v[196:199], v[58:61]
	v_mfma_f32_16x16x32_bf16 v[54:57], v[146:149], v[204:207], v[54:57]
	v_mfma_f32_16x16x32_bf16 v[50:53], v[166:169], v[204:207], v[50:53]
	v_mfma_f32_16x16x32_bf16 v[42:45], v[146:149], v[212:215], v[42:45]
	v_mfma_f32_16x16x32_bf16 v[34:37], v[166:169], v[212:215], v[34:37]
	v_mfma_f32_16x16x32_bf16 v[26:29], v[146:149], v[220:223], v[26:29]
	v_mfma_f32_16x16x32_bf16 v[18:21], v[166:169], v[220:223], v[18:21]
	v_mfma_f32_16x16x32_bf16 v[46:49], v[170:173], v[192:195], v[46:49]
	v_mfma_f32_16x16x32_bf16 v[38:41], v[178:181], v[192:195], v[38:41]
	v_mfma_f32_16x16x32_bf16 v[30:33], v[170:173], v[200:203], v[30:33]
	v_mfma_f32_16x16x32_bf16 v[22:25], v[178:181], v[200:203], v[22:25]
	v_mfma_f32_16x16x32_bf16 v[14:17], v[170:173], v[208:211], v[14:17]
	v_mfma_f32_16x16x32_bf16 v[10:13], v[178:181], v[208:211], v[10:13]
	v_mfma_f32_16x16x32_bf16 v[6:9], v[170:173], v[216:219], v[6:9]
	v_mfma_f32_16x16x32_bf16 v[2:5], v[178:181], v[216:219], v[2:5]
	v_mfma_f32_16x16x32_bf16 v[46:49], v[174:177], v[196:199], v[46:49]
	v_mfma_f32_16x16x32_bf16 v[38:41], v[188:191], v[196:199], v[38:41]
	v_mfma_f32_16x16x32_bf16 v[30:33], v[174:177], v[204:207], v[30:33]
	v_mfma_f32_16x16x32_bf16 v[22:25], v[188:191], v[204:207], v[22:25]
	v_mfma_f32_16x16x32_bf16 v[14:17], v[174:177], v[212:215], v[14:17]
	v_mfma_f32_16x16x32_bf16 v[10:13], v[188:191], v[212:215], v[10:13]
	v_mfma_f32_16x16x32_bf16 v[6:9], v[174:177], v[220:223], v[6:9]
	v_mfma_f32_16x16x32_bf16 v[2:5], v[188:191], v[220:223], v[2:5]
	s_barrier
	s_add_i32 s62, 0, 0x18000
	v_add_u32_e32 v134, s62, v152
	s_add_i32 s64, 0, 0x1c000
	ds_read_b128 v[142:145], v134
	ds_read_b128 v[146:149], v134 offset:1024
	ds_read_b128 v[162:165], v134 offset:2048
	ds_read_b128 v[166:169], v134 offset:3072
	v_add_u32_e32 v134, s64, v152
	ds_read_b128 v[170:173], v134
	ds_read_b128 v[174:177], v134 offset:1024
	ds_read_b128 v[178:181], v134 offset:2048
	ds_read_b128 v[188:191], v134 offset:3072
	s_add_u32 s30, s30, 0x20000
	s_addc_u32 s31, s31, 0
	s_mov_b32 m0, s43
	v_lshl_add_u64 v[232:233], s[30:31], 0, v[130:131]
	ds_read_b128 v[192:195], v160 offset:32768
	ds_read_b128 v[196:199], v160 offset:33792
	ds_read_b128 v[200:203], v160 offset:34816
	ds_read_b128 v[204:207], v160 offset:35840
	ds_read_b128 v[208:211], v160 offset:36864
	ds_read_b128 v[212:215], v160 offset:37888
	ds_read_b128 v[216:219], v160 offset:38912
	ds_read_b128 v[220:223], v160 offset:39936
	global_load_lds_dwordx4 v[232:233], off
	v_lshl_add_u64 v[232:233], s[30:31], 0, v[132:133]
	s_mov_b32 m0, s44
	s_nop 0
	global_load_lds_dwordx4 v[232:233], off
	s_waitcnt vmcnt(8)
	s_waitcnt lgkmcnt(0)
	s_barrier
	s_waitcnt lgkmcnt(0)
	v_mfma_f32_16x16x32_bf16 v[126:129], v[142:145], v[192:195], v[126:129]
	v_mfma_f32_16x16x32_bf16 v[122:125], v[162:165], v[192:195], v[122:125]
	v_mfma_f32_16x16x32_bf16 v[118:121], v[142:145], v[200:203], v[118:121]
	v_mfma_f32_16x16x32_bf16 v[114:117], v[162:165], v[200:203], v[114:117]
	v_mfma_f32_16x16x32_bf16 v[106:109], v[142:145], v[208:211], v[106:109]
	v_mfma_f32_16x16x32_bf16 v[98:101], v[162:165], v[208:211], v[98:101]
	v_mfma_f32_16x16x32_bf16 v[90:93], v[142:145], v[216:219], v[90:93]
	v_mfma_f32_16x16x32_bf16 v[82:85], v[162:165], v[216:219], v[82:85]
	v_mfma_f32_16x16x32_bf16 v[126:129], v[146:149], v[196:199], v[126:129]
	v_mfma_f32_16x16x32_bf16 v[122:125], v[166:169], v[196:199], v[122:125]
	v_mfma_f32_16x16x32_bf16 v[118:121], v[146:149], v[204:207], v[118:121]
	v_mfma_f32_16x16x32_bf16 v[114:117], v[166:169], v[204:207], v[114:117]
	v_mfma_f32_16x16x32_bf16 v[106:109], v[146:149], v[212:215], v[106:109]
	v_mfma_f32_16x16x32_bf16 v[98:101], v[166:169], v[212:215], v[98:101]
	v_mfma_f32_16x16x32_bf16 v[90:93], v[146:149], v[220:223], v[90:93]
	v_mfma_f32_16x16x32_bf16 v[82:85], v[166:169], v[220:223], v[82:85]
	v_mfma_f32_16x16x32_bf16 v[110:113], v[170:173], v[192:195], v[110:113]
	v_mfma_f32_16x16x32_bf16 v[102:105], v[178:181], v[192:195], v[102:105]
	v_mfma_f32_16x16x32_bf16 v[94:97], v[170:173], v[200:203], v[94:97]
	v_mfma_f32_16x16x32_bf16 v[86:89], v[178:181], v[200:203], v[86:89]
	v_mfma_f32_16x16x32_bf16 v[78:81], v[170:173], v[208:211], v[78:81]
	v_mfma_f32_16x16x32_bf16 v[74:77], v[178:181], v[208:211], v[74:77]
	v_mfma_f32_16x16x32_bf16 v[70:73], v[170:173], v[216:219], v[70:73]
	v_mfma_f32_16x16x32_bf16 v[66:69], v[178:181], v[216:219], v[66:69]
	v_mfma_f32_16x16x32_bf16 v[110:113], v[174:177], v[196:199], v[110:113]
	v_mfma_f32_16x16x32_bf16 v[102:105], v[188:191], v[196:199], v[102:105]
	v_mfma_f32_16x16x32_bf16 v[94:97], v[174:177], v[204:207], v[94:97]
	v_mfma_f32_16x16x32_bf16 v[86:89], v[188:191], v[204:207], v[86:89]
	v_mfma_f32_16x16x32_bf16 v[78:81], v[174:177], v[212:215], v[78:81]
	v_mfma_f32_16x16x32_bf16 v[74:77], v[188:191], v[212:215], v[74:77]
	v_mfma_f32_16x16x32_bf16 v[70:73], v[174:177], v[220:223], v[70:73]
	v_mfma_f32_16x16x32_bf16 v[66:69], v[188:191], v[220:223], v[66:69]
	s_barrier
; #define PG8_STAGE(bufoff, gbase) do { _Pragma("unroll") for (int _i = 0; _i < 2; ++_i) \
;         __builtin_amdgcn_global_load_lds((const unsigned*)((const char*)(gbase) + voff[_i]), (LAS unsigned*)(lds + (bufoff) + ldsw + _i * 8192), 16, 0, 0); } while (0)
; #define PG8_LDA(dst, b, h) do { _Pragma("unroll") for (int m = 0; m < 4; ++m) _Pragma("unroll") for (int k = 0; k < 2; ++k) dst[m][k] = *(const LAS bf16x8*)(lds + PG8_SA(b, h) + aoff + m * 2048 + k * 1024); } while (0)
; #define PG8_LDB(dst, b, h) do { _Pragma("unroll") for (int n = 0; n < 2; ++n) _Pragma("unroll") for (int k = 0; k < 2; ++k) dst[n][k] = *(const LAS bf16x8*)(lds + PG8_SB(b, h) + boff + n * 2048 + k * 1024); } while (0)
; #define PG8_MMA(ai, bj, At, Bt) do { __builtin_amdgcn_s_setprio(1); _Pragma("unroll") for (int m = 0; m < 4; ++m) _Pragma("unroll") for (int n = 0; n < 2; ++n) _Pragma("unroll") for (int k = 0; k < 2; ++k) \
;         acc[ai][bj][m][n] = __builtin_amdgcn_mfma_f32_16x16x32_bf16(Bt[n][k], At[m][k], acc[ai][bj][m][n], 0, 0, 0); __builtin_amdgcn_s_setprio(0); } while (0)
; #define PG8_WAIT_V(n) asm volatile("s_waitcnt vmcnt(" #n ")" ::: "memory")
; #define PG8_WAIT_L(n) asm volatile("s_waitcnt lgkmcnt(" #n ")" ::: "memory")
; #define PG8_BAR __builtin_amdgcn_s_barrier()
; #define PG8_SCHED __builtin_amdgcn_sched_barrier(0)
; template <int EPI> ...
;     ...
;             PG8_LDB(B0, 1, 0); PG8_LDB(B1, 1, 1); PG8_SCHED; PG8_LDA(At, 1, 0); PG8_STAGE(PG8_SA(0, 1), a2 + hstep);
;             PG8_WAIT_V(8); PG8_WAIT_L(0); PG8_BAR; PG8_MMA(0, 0, At, B0); PG8_MMA(0, 1, At, B1); PG8_BAR; PG8_SCHED;
;             PG8_LDA(At, 1, 1); PG8_STAGE(PG8_SB(1, 0), b3); PG8_STAGE(PG8_SB(1, 1), b3 + hstep); PG8_STAGE(PG8_SA(1, 0), a3);
;             PG8_WAIT_V(8); PG8_WAIT_L(0); PG8_BAR; PG8_MMA(1, 0, At, B0); PG8_MMA(1, 1, At, B1); PG8_BAR; PG8_SCHED;
;         }
	s_add_i32 s30, s62, s40
	v_lshl_add_u64 v[224:225], v[224:225], 0, s[10:11]
	s_mov_b32 m0, s30
	ds_read_b128 v[192:195], v160 offset:49152
	ds_read_b128 v[196:199], v160 offset:50176
	ds_read_b128 v[200:203], v160 offset:51200
	ds_read_b128 v[204:207], v160 offset:52224
	ds_read_b128 v[208:211], v160 offset:53248
	ds_read_b128 v[212:215], v160 offset:54272
	ds_read_b128 v[216:219], v160 offset:55296
	ds_read_b128 v[220:223], v160 offset:56320
	global_load_lds_dwordx4 v[224:225], off
	s_add_i32 m0, s30, 0x2000
	s_add_u32 s28, s28, 0x20080
	v_lshl_add_u64 v[224:225], v[226:227], 0, s[10:11]
	s_addc_u32 s29, s29, 0
	s_add_i32 s30, s64, s40
	global_load_lds_dwordx4 v[224:225], off
	v_lshl_add_u64 v[224:225], s[28:29], 0, v[130:131]
	s_mov_b32 m0, s30
	s_nop 0
	global_load_lds_dwordx4 v[224:225], off
	v_lshl_add_u64 v[224:225], s[28:29], 0, v[132:133]
	s_add_i32 m0, s30, 0x2000
	s_nop 0
	global_load_lds_dwordx4 v[224:225], off
	v_lshl_add_u64 v[224:225], v[228:229], 0, s[10:11]
	s_mov_b32 m0, s45
	s_nop 0
	global_load_lds_dwordx4 v[224:225], off
	v_lshl_add_u64 v[224:225], v[230:231], 0, s[10:11]
	s_mov_b32 m0, s46
	s_nop 0
	global_load_lds_dwordx4 v[224:225], off
	s_waitcnt vmcnt(8)
	s_waitcnt lgkmcnt(0)
	s_barrier
	s_waitcnt lgkmcnt(0)
	v_mfma_f32_16x16x32_bf16 v[62:65], v[142:145], v[192:195], v[62:65]
	v_mfma_f32_16x16x32_bf16 v[58:61], v[162:165], v[192:195], v[58:61]
	v_mfma_f32_16x16x32_bf16 v[54:57], v[142:145], v[200:203], v[54:57]
	v_mfma_f32_16x16x32_bf16 v[50:53], v[162:165], v[200:203], v[50:53]
	v_mfma_f32_16x16x32_bf16 v[42:45], v[142:145], v[208:211], v[42:45]
	v_mfma_f32_16x16x32_bf16 v[34:37], v[162:165], v[208:211], v[34:37]
	v_mfma_f32_16x16x32_bf16 v[26:29], v[142:145], v[216:219], v[26:29]
	v_mfma_f32_16x16x32_bf16 v[18:21], v[162:165], v[216:219], v[18:21]
	v_mfma_f32_16x16x32_bf16 v[62:65], v[146:149], v[196:199], v[62:65]
	v_mfma_f32_16x16x32_bf16 v[58:61], v[166:169], v[196:199], v[58:61]
	v_mfma_f32_16x16x32_bf16 v[54:57], v[146:149], v[204:207], v[54:57]
	v_mfma_f32_16x16x32_bf16 v[50:53], v[166:169], v[204:207], v[50:53]
	v_mfma_f32_16x16x32_bf16 v[42:45], v[146:149], v[212:215], v[42:45]
	v_mfma_f32_16x16x32_bf16 v[34:37], v[166:169], v[212:215], v[34:37]
	v_mfma_f32_16x16x32_bf16 v[26:29], v[146:149], v[220:223], v[26:29]
	v_mfma_f32_16x16x32_bf16 v[18:21], v[166:169], v[220:223], v[18:21]
	v_mfma_f32_16x16x32_bf16 v[46:49], v[170:173], v[192:195], v[46:49]
	v_mfma_f32_16x16x32_bf16 v[38:41], v[178:181], v[192:195], v[38:41]
	v_mfma_f32_16x16x32_bf16 v[30:33], v[170:173], v[200:203], v[30:33]
	v_mfma_f32_16x16x32_bf16 v[22:25], v[178:181], v[200:203], v[22:25]
	v_mfma_f32_16x16x32_bf16 v[14:17], v[170:173], v[208:211], v[14:17]
	v_mfma_f32_16x16x32_bf16 v[10:13], v[178:181], v[208:211], v[10:13]
	v_mfma_f32_16x16x32_bf16 v[6:9], v[170:173], v[216:219], v[6:9]
	v_mfma_f32_16x16x32_bf16 v[2:5], v[178:181], v[216:219], v[2:5]
	v_mfma_f32_16x16x32_bf16 v[46:49], v[174:177], v[196:199], v[46:49]
	v_mfma_f32_16x16x32_bf16 v[38:41], v[188:191], v[196:199], v[38:41]
	v_mfma_f32_16x16x32_bf16 v[30:33], v[174:177], v[204:207], v[30:33]
	v_mfma_f32_16x16x32_bf16 v[22:25], v[188:191], v[204:207], v[22:25]
	v_mfma_f32_16x16x32_bf16 v[14:17], v[174:177], v[212:215], v[14:17]
	v_mfma_f32_16x16x32_bf16 v[10:13], v[188:191], v[212:215], v[10:13]
	v_mfma_f32_16x16x32_bf16 v[6:9], v[174:177], v[220:223], v[6:9]
	v_mfma_f32_16x16x32_bf16 v[2:5], v[188:191], v[220:223], v[2:5]
	s_barrier
	s_add_u32 s26, s26, 0x100
	s_addc_u32 s27, s27, 0
	s_add_u32 s60, s60, 0x100
	s_addc_u32 s61, s61, 0
	s_cmp_ge_u32 s63, s57
	s_mov_b32 s62, s63
	s_cbranch_scc0 .LBB0_656
	s_and_b64 vcc, exec, s[12:13]
	s_cbranch_vccz .LBB0_661
	s_barrier
	s_cmp_lt_i32 s0, 0
	s_mov_b64 s[26:27], -1
	s_cbranch_scc1 .LBB0_662

; #define PG8_STAGE(bufoff, gbase) do { _Pragma("unroll") for (int _i = 0; _i < 2; ++_i) \
;         __builtin_amdgcn_global_load_lds((const unsigned*)((const char*)(gbase) + voff[_i]), (LAS unsigned*)(lds + (bufoff) + ldsw + _i * 8192), 16, 0, 0); } while (0)
; #define PG8_LDA(dst, b, h) do { _Pragma("unroll") for (int m = 0; m < 4; ++m) _Pragma("unroll") for (int k = 0; k < 2; ++k) dst[m][k] = *(const LAS bf16x8*)(lds + PG8_SA(b, h) + aoff + m * 2048 + k * 1024); } while (0)
; #define PG8_LDB(dst, b, h) do { _Pragma("unroll") for (int n = 0; n < 2; ++n) _Pragma("unroll") for (int k = 0; k < 2; ++k) dst[n][k] = *(const LAS bf16x8*)(lds + PG8_SB(b, h) + boff + n * 2048 + k * 1024); } while (0)
; #define PG8_MMA(ai, bj, At, Bt) do { __builtin_amdgcn_s_setprio(1); _Pragma("unroll") for (int m = 0; m < 4; ++m) _Pragma("unroll") for (int n = 0; n < 2; ++n) _Pragma("unroll") for (int k = 0; k < 2; ++k) \
;         acc[ai][bj][m][n] = __builtin_amdgcn_mfma_f32_16x16x32_bf16(Bt[n][k], At[m][k], acc[ai][bj][m][n], 0, 0, 0); __builtin_amdgcn_s_setprio(0); } while (0)
; #define PG8_WAIT_V(n) asm volatile("s_waitcnt vmcnt(" #n ")" ::: "memory")
; #define PG8_WAIT_L(n) asm volatile("s_waitcnt lgkmcnt(" #n ")" ::: "memory")
; #define PG8_BAR __builtin_amdgcn_s_barrier()
; #define PG8_SCHED __builtin_amdgcn_sched_barrier(0)
; template <int EPI> ...
;     ...
;         for (int t = 0; t < cnk; t += 2) {
;             const bool last = (t == cnk - 2);
;             const char* a1 = cA + (size_t)(t + 1) * kstep;
;             const char* a2 = last ? nA : cA + (size_t)(t + 2) * kstep; const char* b2 = last ? nB : cB + (size_t)(t + 2) * kstep;
;             const char* a3 = a2 + kstep; const char* b3 = b2 + kstep;
;             PG8_LDB(B0, 0, 0); PG8_LDB(B1, 0, 1); PG8_SCHED; PG8_LDA(At, 0, 0); PG8_STAGE(PG8_SA(1, 1), a1 + hstep);
;             PG8_WAIT_V(8); PG8_WAIT_L(0); PG8_BAR; PG8_MMA(0, 0, At, B0); PG8_MMA(0, 1, At, B1); PG8_BAR; PG8_SCHED;
;             PG8_LDA(At, 0, 1); PG8_STAGE(PG8_SB(0, 0), b2); PG8_STAGE(PG8_SB(0, 1), b2 + hstep); PG8_STAGE(PG8_SA(0, 0), a2);
;             PG8_WAIT_V(8); PG8_WAIT_L(0); PG8_BAR; PG8_MMA(1, 0, At, B0); PG8_MMA(1, 1, At, B1); PG8_BAR; PG8_SCHED;
.LBB0_737:
	ds_read_b128 v[142:145], v153
	ds_read_b128 v[146:149], v153 offset:1024
	ds_read_b128 v[156:159], v153 offset:2048
	ds_read_b128 v[160:163], v153 offset:3072
	ds_read_b128 v[164:167], v154
	ds_read_b128 v[168:171], v154 offset:1024
	ds_read_b128 v[172:175], v154 offset:2048
	ds_read_b128 v[176:179], v154 offset:3072
	s_add_u32 s26, s24, 0xfffe0080
	s_addc_u32 s27, s25, -1
	s_cmp_eq_u32 s52, 4
	s_cselect_b32 s29, s17, s27
	s_cselect_b32 s28, s48, s26
	s_cselect_b32 s27, s15, s51
	s_cselect_b32 s26, s49, s50
	v_lshl_add_u64 v[180:181], s[24:25], 0, v[134:135]
	s_add_i32 m0, s23, 0xc000
	ds_read_b128 v[188:191], v155
	ds_read_b128 v[192:195], v155 offset:1024
	ds_read_b128 v[196:199], v155 offset:2048
	ds_read_b128 v[200:203], v155 offset:3072
	ds_read_b128 v[204:207], v155 offset:4096
	ds_read_b128 v[208:211], v155 offset:5120
	ds_read_b128 v[212:215], v155 offset:6144
	ds_read_b128 v[216:219], v155 offset:7168
	global_load_lds_dwordx4 v[180:181], off
	v_lshl_add_u64 v[180:181], s[24:25], 0, v[136:137]
	s_add_i32 m0, s23, 0xe000
	s_nop 0
	global_load_lds_dwordx4 v[180:181], off
	s_waitcnt vmcnt(8)
	s_waitcnt lgkmcnt(0)
	s_barrier
	s_waitcnt lgkmcnt(0)
	v_mfma_f32_16x16x32_bf16 v[126:129], v[142:145], v[188:191], v[126:129]
	v_mfma_f32_16x16x32_bf16 v[122:125], v[156:159], v[188:191], v[122:125]
	v_mfma_f32_16x16x32_bf16 v[110:113], v[142:145], v[196:199], v[110:113]
	v_mfma_f32_16x16x32_bf16 v[106:109], v[156:159], v[196:199], v[106:109]
	v_mfma_f32_16x16x32_bf16 v[94:97], v[142:145], v[204:207], v[94:97]
	v_mfma_f32_16x16x32_bf16 v[90:93], v[156:159], v[204:207], v[90:93]
	v_mfma_f32_16x16x32_bf16 v[78:81], v[142:145], v[212:215], v[78:81]
	v_mfma_f32_16x16x32_bf16 v[74:77], v[156:159], v[212:215], v[74:77]
	v_mfma_f32_16x16x32_bf16 v[126:129], v[146:149], v[192:195], v[126:129]
	v_mfma_f32_16x16x32_bf16 v[122:125], v[160:163], v[192:195], v[122:125]
	v_mfma_f32_16x16x32_bf16 v[110:113], v[146:149], v[200:203], v[110:113]
	v_mfma_f32_16x16x32_bf16 v[106:109], v[160:163], v[200:203], v[106:109]
	v_mfma_f32_16x16x32_bf16 v[94:97], v[146:149], v[208:211], v[94:97]
	v_mfma_f32_16x16x32_bf16 v[90:93], v[160:163], v[208:211], v[90:93]
	v_mfma_f32_16x16x32_bf16 v[78:81], v[146:149], v[216:219], v[78:81]
	v_mfma_f32_16x16x32_bf16 v[74:77], v[160:163], v[216:219], v[74:77]
	v_mfma_f32_16x16x32_bf16 v[118:121], v[164:167], v[188:191], v[118:121]
	v_mfma_f32_16x16x32_bf16 v[114:117], v[172:175], v[188:191], v[114:117]
	v_mfma_f32_16x16x32_bf16 v[102:105], v[164:167], v[196:199], v[102:105]
	v_mfma_f32_16x16x32_bf16 v[98:101], v[172:175], v[196:199], v[98:101]
	v_mfma_f32_16x16x32_bf16 v[86:89], v[164:167], v[204:207], v[86:89]
	v_mfma_f32_16x16x32_bf16 v[82:85], v[172:175], v[204:207], v[82:85]
	v_mfma_f32_16x16x32_bf16 v[70:73], v[164:167], v[212:215], v[70:73]
	v_mfma_f32_16x16x32_bf16 v[66:69], v[172:175], v[212:215], v[66:69]
	v_mfma_f32_16x16x32_bf16 v[118:121], v[168:171], v[192:195], v[118:121]
	v_mfma_f32_16x16x32_bf16 v[114:117], v[176:179], v[192:195], v[114:117]
	v_mfma_f32_16x16x32_bf16 v[102:105], v[168:171], v[200:203], v[102:105]
	v_mfma_f32_16x16x32_bf16 v[98:101], v[176:179], v[200:203], v[98:101]
	v_mfma_f32_16x16x32_bf16 v[86:89], v[168:171], v[208:211], v[86:89]
	v_mfma_f32_16x16x32_bf16 v[82:85], v[176:179], v[208:211], v[82:85]
	v_mfma_f32_16x16x32_bf16 v[70:73], v[168:171], v[216:219], v[70:73]
	v_mfma_f32_16x16x32_bf16 v[66:69], v[176:179], v[216:219], v[66:69]
	s_barrier
	s_add_i32 s53, s44, s30
	v_lshl_add_u64 v[180:181], s[26:27], 0, v[130:131]
	s_mov_b32 m0, s53
	ds_read_b128 v[188:191], v155 offset:16384
	ds_read_b128 v[192:195], v155 offset:17408
	ds_read_b128 v[196:199], v155 offset:18432
	ds_read_b128 v[200:203], v155 offset:19456
	ds_read_b128 v[204:207], v155 offset:20480
	ds_read_b128 v[208:211], v155 offset:21504
	ds_read_b128 v[212:215], v155 offset:22528
	ds_read_b128 v[216:219], v155 offset:23552
	global_load_lds_dwordx4 v[180:181], off
	s_add_i32 m0, s53, 0x2000
	s_add_u32 s54, s26, 0x20000
	v_lshl_add_u64 v[220:221], s[26:27], 0, v[132:133]
	s_addc_u32 s55, s27, 0
	s_add_i32 s53, s45, s30
	global_load_lds_dwordx4 v[220:221], off
	v_lshl_add_u64 v[222:223], s[54:55], 0, v[130:131]
	s_mov_b32 m0, s53
	v_lshl_add_u64 v[224:225], s[28:29], 0, v[132:133]
	global_load_lds_dwordx4 v[222:223], off
	v_lshl_add_u64 v[222:223], s[54:55], 0, v[132:133]
	s_add_i32 m0, s53, 0x2000
	s_nop 0
	global_load_lds_dwordx4 v[222:223], off
	v_lshl_add_u64 v[222:223], s[28:29], 0, v[130:131]
	s_mov_b32 m0, s23
	s_nop 0
	global_load_lds_dwordx4 v[222:223], off
	s_mov_b32 m0, s31
	s_nop 0
	global_load_lds_dwordx4 v[224:225], off
	s_waitcnt vmcnt(8)
	s_waitcnt lgkmcnt(0)
	s_barrier
; #define PG8_STAGE(bufoff, gbase) do { _Pragma("unroll") for (int _i = 0; _i < 2; ++_i) \
;         __builtin_amdgcn_global_load_lds((const unsigned*)((const char*)(gbase) + voff[_i]), (LAS unsigned*)(lds + (bufoff) + ldsw + _i * 8192), 16, 0, 0); } while (0)
; #define PG8_LDA(dst, b, h) do { _Pragma("unroll") for (int m = 0; m < 4; ++m) _Pragma("unroll") for (int k = 0; k < 2; ++k) dst[m][k] = *(const LAS bf16x8*)(lds + PG8_SA(b, h) + aoff + m * 2048 + k * 1024); } while (0)
; #define PG8_LDB(dst, b, h) do { _Pragma("unroll") for (int n = 0; n < 2; ++n) _Pragma("unroll") for (int k = 0; k < 2; ++k) dst[n][k] = *(const LAS bf16x8*)(lds + PG8_SB(b, h) + boff + n * 2048 + k * 1024); } while (0)
; #define PG8_MMA(ai, bj, At, Bt) do { __builtin_amdgcn_s_setprio(1); _Pragma("unroll") for (int m = 0; m < 4; ++m) _Pragma("unroll") for (int n = 0; n < 2; ++n) _Pragma("unroll") for (int k = 0; k < 2; ++k) \
;         acc[ai][bj][m][n] = __builtin_amdgcn_mfma_f32_16x16x32_bf16(Bt[n][k], At[m][k], acc[ai][bj][m][n], 0, 0, 0); __builtin_amdgcn_s_setprio(0); } while (0)
; #define PG8_WAIT_V(n) asm volatile("s_waitcnt vmcnt(" #n ")" ::: "memory")
; #define PG8_WAIT_L(n) asm volatile("s_waitcnt lgkmcnt(" #n ")" ::: "memory")
; #define PG8_BAR __builtin_amdgcn_s_barrier()
; #define PG8_SCHED __builtin_amdgcn_sched_barrier(0)
; template <int EPI> ...
;     ...
;             PG8_LDA(At, 0, 1); PG8_STAGE(PG8_SB(0, 0), b2); PG8_STAGE(PG8_SB(0, 1), b2 + hstep); PG8_STAGE(PG8_SA(0, 0), a2);
;             PG8_WAIT_V(8); PG8_WAIT_L(0); PG8_BAR; PG8_MMA(1, 0, At, B0); PG8_MMA(1, 1, At, B1); PG8_BAR; PG8_SCHED;
;             PG8_LDB(B0, 1, 0); PG8_LDB(B1, 1, 1); PG8_SCHED; PG8_LDA(At, 1, 0); PG8_STAGE(PG8_SA(0, 1), a2 + hstep);
;             PG8_WAIT_V(8); PG8_WAIT_L(0); PG8_BAR; PG8_MMA(0, 0, At, B0); PG8_MMA(0, 1, At, B1); PG8_BAR; PG8_SCHED;
	s_waitcnt lgkmcnt(0)
	v_mfma_f32_16x16x32_bf16 v[62:65], v[142:145], v[188:191], v[62:65]
	v_mfma_f32_16x16x32_bf16 v[58:61], v[156:159], v[188:191], v[58:61]
	v_mfma_f32_16x16x32_bf16 v[46:49], v[142:145], v[196:199], v[46:49]
	v_mfma_f32_16x16x32_bf16 v[42:45], v[156:159], v[196:199], v[42:45]
	v_mfma_f32_16x16x32_bf16 v[30:33], v[142:145], v[204:207], v[30:33]
	v_mfma_f32_16x16x32_bf16 v[26:29], v[156:159], v[204:207], v[26:29]
	v_mfma_f32_16x16x32_bf16 v[14:17], v[142:145], v[212:215], v[14:17]
	v_mfma_f32_16x16x32_bf16 v[10:13], v[156:159], v[212:215], v[10:13]
	v_mfma_f32_16x16x32_bf16 v[62:65], v[146:149], v[192:195], v[62:65]
	v_mfma_f32_16x16x32_bf16 v[58:61], v[160:163], v[192:195], v[58:61]
	v_mfma_f32_16x16x32_bf16 v[46:49], v[146:149], v[200:203], v[46:49]
	v_mfma_f32_16x16x32_bf16 v[42:45], v[160:163], v[200:203], v[42:45]
	v_mfma_f32_16x16x32_bf16 v[30:33], v[146:149], v[208:211], v[30:33]
	v_mfma_f32_16x16x32_bf16 v[26:29], v[160:163], v[208:211], v[26:29]
	v_mfma_f32_16x16x32_bf16 v[14:17], v[146:149], v[216:219], v[14:17]
	v_mfma_f32_16x16x32_bf16 v[10:13], v[160:163], v[216:219], v[10:13]
	v_mfma_f32_16x16x32_bf16 v[54:57], v[164:167], v[188:191], v[54:57]
	v_mfma_f32_16x16x32_bf16 v[50:53], v[172:175], v[188:191], v[50:53]
	v_mfma_f32_16x16x32_bf16 v[38:41], v[164:167], v[196:199], v[38:41]
	v_mfma_f32_16x16x32_bf16 v[34:37], v[172:175], v[196:199], v[34:37]
	v_mfma_f32_16x16x32_bf16 v[22:25], v[164:167], v[204:207], v[22:25]
	v_mfma_f32_16x16x32_bf16 v[18:21], v[172:175], v[204:207], v[18:21]
	v_mfma_f32_16x16x32_bf16 v[6:9], v[164:167], v[212:215], v[6:9]
	v_mfma_f32_16x16x32_bf16 v[2:5], v[172:175], v[212:215], v[2:5]
	v_mfma_f32_16x16x32_bf16 v[54:57], v[168:171], v[192:195], v[54:57]
	v_mfma_f32_16x16x32_bf16 v[50:53], v[176:179], v[192:195], v[50:53]
	v_mfma_f32_16x16x32_bf16 v[38:41], v[168:171], v[200:203], v[38:41]
	v_mfma_f32_16x16x32_bf16 v[34:37], v[176:179], v[200:203], v[34:37]
	v_mfma_f32_16x16x32_bf16 v[22:25], v[168:171], v[208:211], v[22:25]
	v_mfma_f32_16x16x32_bf16 v[18:21], v[176:179], v[208:211], v[18:21]
	v_mfma_f32_16x16x32_bf16 v[6:9], v[168:171], v[216:219], v[6:9]
	v_mfma_f32_16x16x32_bf16 v[2:5], v[176:179], v[216:219], v[2:5]
	s_barrier
	s_add_i32 s53, 0, 0x18000
	s_add_i32 s54, 0, 0x1c000
	v_add_u32_e32 v160, s53, v151
	v_add_u32_e32 v176, s54, v151
	ds_read_b128 v[142:145], v160
	ds_read_b128 v[146:149], v160 offset:1024
	ds_read_b128 v[156:159], v160 offset:2048
	ds_read_b128 v[160:163], v160 offset:3072
	ds_read_b128 v[164:167], v176
	ds_read_b128 v[168:171], v176 offset:1024
	ds_read_b128 v[172:175], v176 offset:2048
	ds_read_b128 v[176:179], v176 offset:3072
	s_add_u32 s28, s28, 0x20000
	s_addc_u32 s29, s29, 0
	s_mov_b32 m0, s38
	v_lshl_add_u64 v[226:227], s[28:29], 0, v[130:131]
	ds_read_b128 v[188:191], v155 offset:32768
	ds_read_b128 v[192:195], v155 offset:33792
	ds_read_b128 v[196:199], v155 offset:34816
	ds_read_b128 v[200:203], v155 offset:35840
	ds_read_b128 v[204:207], v155 offset:36864
	ds_read_b128 v[208:211], v155 offset:37888
	ds_read_b128 v[212:215], v155 offset:38912
	ds_read_b128 v[216:219], v155 offset:39936
	global_load_lds_dwordx4 v[226:227], off
	v_lshl_add_u64 v[226:227], s[28:29], 0, v[132:133]
	s_mov_b32 m0, s39
	s_nop 0
	global_load_lds_dwordx4 v[226:227], off
	s_waitcnt vmcnt(8)
	s_waitcnt lgkmcnt(0)
	s_barrier
	s_waitcnt lgkmcnt(0)
	v_mfma_f32_16x16x32_bf16 v[126:129], v[142:145], v[188:191], v[126:129]
	v_mfma_f32_16x16x32_bf16 v[122:125], v[156:159], v[188:191], v[122:125]
	v_mfma_f32_16x16x32_bf16 v[110:113], v[142:145], v[196:199], v[110:113]
	v_mfma_f32_16x16x32_bf16 v[106:109], v[156:159], v[196:199], v[106:109]
	v_mfma_f32_16x16x32_bf16 v[94:97], v[142:145], v[204:207], v[94:97]
	v_mfma_f32_16x16x32_bf16 v[90:93], v[156:159], v[204:207], v[90:93]
	v_mfma_f32_16x16x32_bf16 v[78:81], v[142:145], v[212:215], v[78:81]
	v_mfma_f32_16x16x32_bf16 v[74:77], v[156:159], v[212:215], v[74:77]
	v_mfma_f32_16x16x32_bf16 v[126:129], v[146:149], v[192:195], v[126:129]
	v_mfma_f32_16x16x32_bf16 v[122:125], v[160:163], v[192:195], v[122:125]
	v_mfma_f32_16x16x32_bf16 v[110:113], v[146:149], v[200:203], v[110:113]
	v_mfma_f32_16x16x32_bf16 v[106:109], v[160:163], v[200:203], v[106:109]
	v_mfma_f32_16x16x32_bf16 v[94:97], v[146:149], v[208:211], v[94:97]
	v_mfma_f32_16x16x32_bf16 v[90:93], v[160:163], v[208:211], v[90:93]
	v_mfma_f32_16x16x32_bf16 v[78:81], v[146:149], v[216:219], v[78:81]
	v_mfma_f32_16x16x32_bf16 v[74:77], v[160:163], v[216:219], v[74:77]
	v_mfma_f32_16x16x32_bf16 v[118:121], v[164:167], v[188:191], v[118:121]
	v_mfma_f32_16x16x32_bf16 v[114:117], v[172:175], v[188:191], v[114:117]
	v_mfma_f32_16x16x32_bf16 v[102:105], v[164:167], v[196:199], v[102:105]
	v_mfma_f32_16x16x32_bf16 v[98:101], v[172:175], v[196:199], v[98:101]
	v_mfma_f32_16x16x32_bf16 v[86:89], v[164:167], v[204:207], v[86:89]
	v_mfma_f32_16x16x32_bf16 v[82:85], v[172:175], v[204:207], v[82:85]
	v_mfma_f32_16x16x32_bf16 v[70:73], v[164:167], v[212:215], v[70:73]
	v_mfma_f32_16x16x32_bf16 v[66:69], v[172:175], v[212:215], v[66:69]
	v_mfma_f32_16x16x32_bf16 v[118:121], v[168:171], v[192:195], v[118:121]
	v_mfma_f32_16x16x32_bf16 v[114:117], v[176:179], v[192:195], v[114:117]
	v_mfma_f32_16x16x32_bf16 v[102:105], v[168:171], v[200:203], v[102:105]
	v_mfma_f32_16x16x32_bf16 v[98:101], v[176:179], v[200:203], v[98:101]
	v_mfma_f32_16x16x32_bf16 v[86:89], v[168:171], v[208:211], v[86:89]
	v_mfma_f32_16x16x32_bf16 v[82:85], v[176:179], v[208:211], v[82:85]
	v_mfma_f32_16x16x32_bf16 v[70:73], v[168:171], v[216:219], v[70:73]
	v_mfma_f32_16x16x32_bf16 v[66:69], v[176:179], v[216:219], v[66:69]
	s_barrier
; #define PG8_STAGE(bufoff, gbase) do { _Pragma("unroll") for (int _i = 0; _i < 2; ++_i) \
;         __builtin_amdgcn_global_load_lds((const unsigned*)((const char*)(gbase) + voff[_i]), (LAS unsigned*)(lds + (bufoff) + ldsw + _i * 8192), 16, 0, 0); } while (0)
; #define PG8_LDA(dst, b, h) do { _Pragma("unroll") for (int m = 0; m < 4; ++m) _Pragma("unroll") for (int k = 0; k < 2; ++k) dst[m][k] = *(const LAS bf16x8*)(lds + PG8_SA(b, h) + aoff + m * 2048 + k * 1024); } while (0)
; #define PG8_LDB(dst, b, h) do { _Pragma("unroll") for (int n = 0; n < 2; ++n) _Pragma("unroll") for (int k = 0; k < 2; ++k) dst[n][k] = *(const LAS bf16x8*)(lds + PG8_SB(b, h) + boff + n * 2048 + k * 1024); } while (0)
; #define PG8_MMA(ai, bj, At, Bt) do { __builtin_amdgcn_s_setprio(1); _Pragma("unroll") for (int m = 0; m < 4; ++m) _Pragma("unroll") for (int n = 0; n < 2; ++n) _Pragma("unroll") for (int k = 0; k < 2; ++k) \
;         acc[ai][bj][m][n] = __builtin_amdgcn_mfma_f32_16x16x32_bf16(Bt[n][k], At[m][k], acc[ai][bj][m][n], 0, 0, 0); __builtin_amdgcn_s_setprio(0); } while (0)
; #define PG8_WAIT_V(n) asm volatile("s_waitcnt vmcnt(" #n ")" ::: "memory")
; #define PG8_WAIT_L(n) asm volatile("s_waitcnt lgkmcnt(" #n ")" ::: "memory")
; #define PG8_BAR __builtin_amdgcn_s_barrier()
; #define PG8_SCHED __builtin_amdgcn_sched_barrier(0)
; template <int EPI> ...
;     ...
;             PG8_LDB(B0, 1, 0); PG8_LDB(B1, 1, 1); PG8_SCHED; PG8_LDA(At, 1, 0); PG8_STAGE(PG8_SA(0, 1), a2 + hstep);
;             PG8_WAIT_V(8); PG8_WAIT_L(0); PG8_BAR; PG8_MMA(0, 0, At, B0); PG8_MMA(0, 1, At, B1); PG8_BAR; PG8_SCHED;
;             PG8_LDA(At, 1, 1); PG8_STAGE(PG8_SB(1, 0), b3); PG8_STAGE(PG8_SB(1, 1), b3 + hstep); PG8_STAGE(PG8_SA(1, 0), a3);
;             PG8_WAIT_V(8); PG8_WAIT_L(0); PG8_BAR; PG8_MMA(1, 0, At, B0); PG8_MMA(1, 1, At, B1); PG8_BAR; PG8_SCHED;
;         }
	s_add_i32 s28, s53, s30
	v_lshl_add_u64 v[180:181], v[180:181], 0, s[6:7]
	s_mov_b32 m0, s28
	ds_read_b128 v[188:191], v155 offset:49152
	ds_read_b128 v[192:195], v155 offset:50176
	ds_read_b128 v[196:199], v155 offset:51200
	ds_read_b128 v[200:203], v155 offset:52224
	ds_read_b128 v[204:207], v155 offset:53248
	ds_read_b128 v[208:211], v155 offset:54272
	ds_read_b128 v[212:215], v155 offset:55296
	ds_read_b128 v[216:219], v155 offset:56320
	global_load_lds_dwordx4 v[180:181], off
	s_add_i32 m0, s28, 0x2000
	s_add_u32 s26, s26, 0x20080
	v_lshl_add_u64 v[180:181], v[220:221], 0, s[6:7]
	s_addc_u32 s27, s27, 0
	s_add_i32 s28, s54, s30
	global_load_lds_dwordx4 v[180:181], off
	v_lshl_add_u64 v[180:181], s[26:27], 0, v[130:131]
	s_mov_b32 m0, s28
	s_nop 0
	global_load_lds_dwordx4 v[180:181], off
	v_lshl_add_u64 v[180:181], s[26:27], 0, v[132:133]
	s_add_i32 m0, s28, 0x2000
	s_nop 0
	global_load_lds_dwordx4 v[180:181], off
	v_lshl_add_u64 v[180:181], v[222:223], 0, s[6:7]
	s_mov_b32 m0, s41
	s_nop 0
	global_load_lds_dwordx4 v[180:181], off
	v_lshl_add_u64 v[180:181], v[224:225], 0, s[6:7]
	s_mov_b32 m0, s42
	s_nop 0
	global_load_lds_dwordx4 v[180:181], off
	s_waitcnt vmcnt(8)
	s_waitcnt lgkmcnt(0)
	s_barrier
	s_waitcnt lgkmcnt(0)
	v_mfma_f32_16x16x32_bf16 v[62:65], v[142:145], v[188:191], v[62:65]
	v_mfma_f32_16x16x32_bf16 v[58:61], v[156:159], v[188:191], v[58:61]
	v_mfma_f32_16x16x32_bf16 v[46:49], v[142:145], v[196:199], v[46:49]
	v_mfma_f32_16x16x32_bf16 v[42:45], v[156:159], v[196:199], v[42:45]
	v_mfma_f32_16x16x32_bf16 v[30:33], v[142:145], v[204:207], v[30:33]
	v_mfma_f32_16x16x32_bf16 v[26:29], v[156:159], v[204:207], v[26:29]
	v_mfma_f32_16x16x32_bf16 v[14:17], v[142:145], v[212:215], v[14:17]
	v_mfma_f32_16x16x32_bf16 v[10:13], v[156:159], v[212:215], v[10:13]
	v_mfma_f32_16x16x32_bf16 v[62:65], v[146:149], v[192:195], v[62:65]
	v_mfma_f32_16x16x32_bf16 v[58:61], v[160:163], v[192:195], v[58:61]
	v_mfma_f32_16x16x32_bf16 v[46:49], v[146:149], v[200:203], v[46:49]
	v_mfma_f32_16x16x32_bf16 v[42:45], v[160:163], v[200:203], v[42:45]
	v_mfma_f32_16x16x32_bf16 v[30:33], v[146:149], v[208:211], v[30:33]
	v_mfma_f32_16x16x32_bf16 v[26:29], v[160:163], v[208:211], v[26:29]
	v_mfma_f32_16x16x32_bf16 v[14:17], v[146:149], v[216:219], v[14:17]
	v_mfma_f32_16x16x32_bf16 v[10:13], v[160:163], v[216:219], v[10:13]
	v_mfma_f32_16x16x32_bf16 v[54:57], v[164:167], v[188:191], v[54:57]
	v_mfma_f32_16x16x32_bf16 v[50:53], v[172:175], v[188:191], v[50:53]
	v_mfma_f32_16x16x32_bf16 v[38:41], v[164:167], v[196:199], v[38:41]
	v_mfma_f32_16x16x32_bf16 v[34:37], v[172:175], v[196:199], v[34:37]
	v_mfma_f32_16x16x32_bf16 v[22:25], v[164:167], v[204:207], v[22:25]
	v_mfma_f32_16x16x32_bf16 v[18:21], v[172:175], v[204:207], v[18:21]
	v_mfma_f32_16x16x32_bf16 v[6:9], v[164:167], v[212:215], v[6:9]
	v_mfma_f32_16x16x32_bf16 v[2:5], v[172:175], v[212:215], v[2:5]
	v_mfma_f32_16x16x32_bf16 v[54:57], v[168:171], v[192:195], v[54:57]
	v_mfma_f32_16x16x32_bf16 v[50:53], v[176:179], v[192:195], v[50:53]
	v_mfma_f32_16x16x32_bf16 v[38:41], v[168:171], v[200:203], v[38:41]
	v_mfma_f32_16x16x32_bf16 v[34:37], v[176:179], v[200:203], v[34:37]
	v_mfma_f32_16x16x32_bf16 v[22:25], v[168:171], v[208:211], v[22:25]
	v_mfma_f32_16x16x32_bf16 v[18:21], v[176:179], v[208:211], v[18:21]
	v_mfma_f32_16x16x32_bf16 v[6:9], v[168:171], v[216:219], v[6:9]
	v_mfma_f32_16x16x32_bf16 v[2:5], v[176:179], v[216:219], v[2:5]
	s_barrier
	s_add_i32 s52, s52, 2
	s_add_u32 s24, s24, 0x100
	s_addc_u32 s25, s25, 0
	s_add_u32 s50, s50, 0x100
	s_addc_u32 s51, s51, 0
	s_cmp_gt_u32 s52, 5
	s_cbranch_scc0 .LBB0_737
	s_and_b64 vcc, exec, s[8:9]
	s_cbranch_vccz .LBB0_740
	s_barrier

; #define PG8_STAGE(bufoff, gbase) do { _Pragma("unroll") for (int _i = 0; _i < 2; ++_i) \
;         __builtin_amdgcn_global_load_lds((const unsigned*)((const char*)(gbase) + voff[_i]), (LAS unsigned*)(lds + (bufoff) + ldsw + _i * 8192), 16, 0, 0); } while (0)
; #define PG8_LDA(dst, b, h) do { _Pragma("unroll") for (int m = 0; m < 4; ++m) _Pragma("unroll") for (int k = 0; k < 2; ++k) dst[m][k] = *(const LAS bf16x8*)(lds + PG8_SA(b, h) + aoff + m * 2048 + k * 1024); } while (0)
; #define PG8_LDB(dst, b, h) do { _Pragma("unroll") for (int n = 0; n < 2; ++n) _Pragma("unroll") for (int k = 0; k < 2; ++k) dst[n][k] = *(const LAS bf16x8*)(lds + PG8_SB(b, h) + boff + n * 2048 + k * 1024); } while (0)
; #define PG8_MMA(ai, bj, At, Bt) do { __builtin_amdgcn_s_setprio(1); _Pragma("unroll") for (int m = 0; m < 4; ++m) _Pragma("unroll") for (int n = 0; n < 2; ++n) _Pragma("unroll") for (int k = 0; k < 2; ++k) \
;         acc[ai][bj][m][n] = __builtin_amdgcn_mfma_f32_16x16x32_bf16(Bt[n][k], At[m][k], acc[ai][bj][m][n], 0, 0, 0); __builtin_amdgcn_s_setprio(0); } while (0)
; #define PG8_WAIT_V(n) asm volatile("s_waitcnt vmcnt(" #n ")" ::: "memory")
; #define PG8_WAIT_L(n) asm volatile("s_waitcnt lgkmcnt(" #n ")" ::: "memory")
; #define PG8_BAR __builtin_amdgcn_s_barrier()
; #define PG8_SCHED __builtin_amdgcn_sched_barrier(0)
; template <int EPI> ...
;     ...
;         for (int t = 0; t < cnk; t += 2) {
;             const bool last = (t == cnk - 2);
;             const char* a1 = cA + (size_t)(t + 1) * kstep;
;             const char* a2 = last ? nA : cA + (size_t)(t + 2) * kstep; const char* b2 = last ? nB : cB + (size_t)(t + 2) * kstep;
;             const char* a3 = a2 + kstep; const char* b3 = b2 + kstep;
;             PG8_LDB(B0, 0, 0); PG8_LDB(B1, 0, 1); PG8_SCHED; PG8_LDA(At, 0, 0); PG8_STAGE(PG8_SA(1, 1), a1 + hstep);
;             PG8_WAIT_V(8); PG8_WAIT_L(0); PG8_BAR; PG8_MMA(0, 0, At, B0); PG8_MMA(0, 1, At, B1); PG8_BAR; PG8_SCHED;
;             PG8_LDA(At, 0, 1); PG8_STAGE(PG8_SB(0, 0), b2); PG8_STAGE(PG8_SB(0, 1), b2 + hstep); PG8_STAGE(PG8_SA(0, 0), a2);
;             PG8_WAIT_V(8); PG8_WAIT_L(0); PG8_BAR; PG8_MMA(1, 0, At, B0); PG8_MMA(1, 1, At, B1); PG8_BAR; PG8_SCHED;
.LBB0_825:
	ds_read_b128 v[142:145], v152
	ds_read_b128 v[156:159], v152 offset:1024
	ds_read_b128 v[160:163], v152 offset:2048
	ds_read_b128 v[164:167], v152 offset:3072
	ds_read_b128 v[168:171], v153
	ds_read_b128 v[172:175], v153 offset:1024
	ds_read_b128 v[176:179], v153 offset:2048
	ds_read_b128 v[188:191], v153 offset:3072
	s_add_i32 s57, s34, 2
	s_add_u32 s35, s30, 0xfffc0080
	s_addc_u32 s36, s31, -1
	s_cmp_eq_u32 s54, s34
	s_cselect_b32 s34, s53, s55
	s_cselect_b32 s37, s5, s36
	s_cselect_b32 s36, s19, s35
	s_cselect_b32 s35, s17, s56
	v_lshl_add_u64 v[146:147], s[30:31], 0, v[136:137]
	s_add_i32 m0, s7, 0xc000
	ds_read_b128 v[192:195], v154
	ds_read_b128 v[196:199], v154 offset:1024
	ds_read_b128 v[200:203], v154 offset:2048
	ds_read_b128 v[204:207], v154 offset:3072
	ds_read_b128 v[208:211], v154 offset:4096
	ds_read_b128 v[212:215], v154 offset:5120
	ds_read_b128 v[216:219], v154 offset:6144
	ds_read_b128 v[220:223], v154 offset:7168
	global_load_lds_dwordx4 v[146:147], off
	v_lshl_add_u64 v[146:147], s[30:31], 0, v[138:139]
	s_add_i32 m0, s7, 0xe000
	s_nop 0
	global_load_lds_dwordx4 v[146:147], off
	s_waitcnt vmcnt(8)
	s_waitcnt lgkmcnt(0)
	s_barrier
	s_waitcnt lgkmcnt(0)
	v_mfma_f32_16x16x32_bf16 v[126:129], v[142:145], v[192:195], v[126:129]
	v_mfma_f32_16x16x32_bf16 v[122:125], v[160:163], v[192:195], v[122:125]
	v_mfma_f32_16x16x32_bf16 v[118:121], v[142:145], v[200:203], v[118:121]
	v_mfma_f32_16x16x32_bf16 v[114:117], v[160:163], v[200:203], v[114:117]
	v_mfma_f32_16x16x32_bf16 v[106:109], v[142:145], v[208:211], v[106:109]
	v_mfma_f32_16x16x32_bf16 v[98:101], v[160:163], v[208:211], v[98:101]
	v_mfma_f32_16x16x32_bf16 v[90:93], v[142:145], v[216:219], v[90:93]
	v_mfma_f32_16x16x32_bf16 v[82:85], v[160:163], v[216:219], v[82:85]
	v_mfma_f32_16x16x32_bf16 v[126:129], v[156:159], v[196:199], v[126:129]
	v_mfma_f32_16x16x32_bf16 v[122:125], v[164:167], v[196:199], v[122:125]
	v_mfma_f32_16x16x32_bf16 v[118:121], v[156:159], v[204:207], v[118:121]
	v_mfma_f32_16x16x32_bf16 v[114:117], v[164:167], v[204:207], v[114:117]
	v_mfma_f32_16x16x32_bf16 v[106:109], v[156:159], v[212:215], v[106:109]
	v_mfma_f32_16x16x32_bf16 v[98:101], v[164:167], v[212:215], v[98:101]
	v_mfma_f32_16x16x32_bf16 v[90:93], v[156:159], v[220:223], v[90:93]
	v_mfma_f32_16x16x32_bf16 v[82:85], v[164:167], v[220:223], v[82:85]
	v_mfma_f32_16x16x32_bf16 v[110:113], v[168:171], v[192:195], v[110:113]
	v_mfma_f32_16x16x32_bf16 v[102:105], v[176:179], v[192:195], v[102:105]
	v_mfma_f32_16x16x32_bf16 v[94:97], v[168:171], v[200:203], v[94:97]
	v_mfma_f32_16x16x32_bf16 v[86:89], v[176:179], v[200:203], v[86:89]
	v_mfma_f32_16x16x32_bf16 v[78:81], v[168:171], v[208:211], v[78:81]
	v_mfma_f32_16x16x32_bf16 v[74:77], v[176:179], v[208:211], v[74:77]
	v_mfma_f32_16x16x32_bf16 v[70:73], v[168:171], v[216:219], v[70:73]
	v_mfma_f32_16x16x32_bf16 v[66:69], v[176:179], v[216:219], v[66:69]
	v_mfma_f32_16x16x32_bf16 v[110:113], v[172:175], v[196:199], v[110:113]
	v_mfma_f32_16x16x32_bf16 v[102:105], v[188:191], v[196:199], v[102:105]
	v_mfma_f32_16x16x32_bf16 v[94:97], v[172:175], v[204:207], v[94:97]
	v_mfma_f32_16x16x32_bf16 v[86:89], v[188:191], v[204:207], v[86:89]
	v_mfma_f32_16x16x32_bf16 v[78:81], v[172:175], v[212:215], v[78:81]
	v_mfma_f32_16x16x32_bf16 v[74:77], v[188:191], v[212:215], v[74:77]
	v_mfma_f32_16x16x32_bf16 v[70:73], v[172:175], v[220:223], v[70:73]
	v_mfma_f32_16x16x32_bf16 v[66:69], v[188:191], v[220:223], v[66:69]
	s_barrier
	s_add_i32 s58, s46, s39
	v_lshl_add_u64 v[146:147], s[34:35], 0, v[130:131]
	s_mov_b32 m0, s58
	ds_read_b128 v[192:195], v154 offset:16384
	ds_read_b128 v[196:199], v154 offset:17408
	ds_read_b128 v[200:203], v154 offset:18432
	ds_read_b128 v[204:207], v154 offset:19456
	ds_read_b128 v[208:211], v154 offset:20480
	ds_read_b128 v[212:215], v154 offset:21504
	ds_read_b128 v[216:219], v154 offset:22528
	ds_read_b128 v[220:223], v154 offset:23552
	global_load_lds_dwordx4 v[146:147], off
	s_add_i32 m0, s58, 0x2000
	s_add_u32 s58, s34, 0x40000
	v_lshl_add_u64 v[180:181], s[34:35], 0, v[132:133]
	s_addc_u32 s59, s35, 0
	s_add_i32 s60, s47, s39
	global_load_lds_dwordx4 v[180:181], off
	v_lshl_add_u64 v[224:225], s[58:59], 0, v[130:131]
	s_mov_b32 m0, s60
	v_lshl_add_u64 v[226:227], s[36:37], 0, v[132:133]
	global_load_lds_dwordx4 v[224:225], off
	v_lshl_add_u64 v[224:225], s[58:59], 0, v[132:133]
	s_add_i32 m0, s60, 0x2000
	s_nop 0
	global_load_lds_dwordx4 v[224:225], off
	v_lshl_add_u64 v[224:225], s[36:37], 0, v[130:131]
	s_mov_b32 m0, s7
	s_nop 0
	global_load_lds_dwordx4 v[224:225], off
	s_mov_b32 m0, s40
	s_nop 0
	global_load_lds_dwordx4 v[226:227], off
	s_waitcnt vmcnt(8)
	s_waitcnt lgkmcnt(0)
	s_barrier
; #define PG8_STAGE(bufoff, gbase) do { _Pragma("unroll") for (int _i = 0; _i < 2; ++_i) \
;         __builtin_amdgcn_global_load_lds((const unsigned*)((const char*)(gbase) + voff[_i]), (LAS unsigned*)(lds + (bufoff) + ldsw + _i * 8192), 16, 0, 0); } while (0)
; #define PG8_LDA(dst, b, h) do { _Pragma("unroll") for (int m = 0; m < 4; ++m) _Pragma("unroll") for (int k = 0; k < 2; ++k) dst[m][k] = *(const LAS bf16x8*)(lds + PG8_SA(b, h) + aoff + m * 2048 + k * 1024); } while (0)
; #define PG8_LDB(dst, b, h) do { _Pragma("unroll") for (int n = 0; n < 2; ++n) _Pragma("unroll") for (int k = 0; k < 2; ++k) dst[n][k] = *(const LAS bf16x8*)(lds + PG8_SB(b, h) + boff + n * 2048 + k * 1024); } while (0)
; #define PG8_MMA(ai, bj, At, Bt) do { __builtin_amdgcn_s_setprio(1); _Pragma("unroll") for (int m = 0; m < 4; ++m) _Pragma("unroll") for (int n = 0; n < 2; ++n) _Pragma("unroll") for (int k = 0; k < 2; ++k) \
;         acc[ai][bj][m][n] = __builtin_amdgcn_mfma_f32_16x16x32_bf16(Bt[n][k], At[m][k], acc[ai][bj][m][n], 0, 0, 0); __builtin_amdgcn_s_setprio(0); } while (0)
; #define PG8_WAIT_V(n) asm volatile("s_waitcnt vmcnt(" #n ")" ::: "memory")
; #define PG8_WAIT_L(n) asm volatile("s_waitcnt lgkmcnt(" #n ")" ::: "memory")
; #define PG8_BAR __builtin_amdgcn_s_barrier()
; #define PG8_SCHED __builtin_amdgcn_sched_barrier(0)
; template <int EPI> ...
;     ...
;             PG8_LDA(At, 0, 1); PG8_STAGE(PG8_SB(0, 0), b2); PG8_STAGE(PG8_SB(0, 1), b2 + hstep); PG8_STAGE(PG8_SA(0, 0), a2);
;             PG8_WAIT_V(8); PG8_WAIT_L(0); PG8_BAR; PG8_MMA(1, 0, At, B0); PG8_MMA(1, 1, At, B1); PG8_BAR; PG8_SCHED;
;             PG8_LDB(B0, 1, 0); PG8_LDB(B1, 1, 1); PG8_SCHED; PG8_LDA(At, 1, 0); PG8_STAGE(PG8_SA(0, 1), a2 + hstep);
;             PG8_WAIT_V(8); PG8_WAIT_L(0); PG8_BAR; PG8_MMA(0, 0, At, B0); PG8_MMA(0, 1, At, B1); PG8_BAR; PG8_SCHED;
	s_waitcnt lgkmcnt(0)
	v_mfma_f32_16x16x32_bf16 v[62:65], v[142:145], v[192:195], v[62:65]
	v_mfma_f32_16x16x32_bf16 v[58:61], v[160:163], v[192:195], v[58:61]
	v_mfma_f32_16x16x32_bf16 v[54:57], v[142:145], v[200:203], v[54:57]
	v_mfma_f32_16x16x32_bf16 v[50:53], v[160:163], v[200:203], v[50:53]
	v_mfma_f32_16x16x32_bf16 v[42:45], v[142:145], v[208:211], v[42:45]
	v_mfma_f32_16x16x32_bf16 v[34:37], v[160:163], v[208:211], v[34:37]
	v_mfma_f32_16x16x32_bf16 v[26:29], v[142:145], v[216:219], v[26:29]
	v_mfma_f32_16x16x32_bf16 v[18:21], v[160:163], v[216:219], v[18:21]
	v_mfma_f32_16x16x32_bf16 v[62:65], v[156:159], v[196:199], v[62:65]
	v_mfma_f32_16x16x32_bf16 v[58:61], v[164:167], v[196:199], v[58:61]
	v_mfma_f32_16x16x32_bf16 v[54:57], v[156:159], v[204:207], v[54:57]
	v_mfma_f32_16x16x32_bf16 v[50:53], v[164:167], v[204:207], v[50:53]
	v_mfma_f32_16x16x32_bf16 v[42:45], v[156:159], v[212:215], v[42:45]
	v_mfma_f32_16x16x32_bf16 v[34:37], v[164:167], v[212:215], v[34:37]
	v_mfma_f32_16x16x32_bf16 v[26:29], v[156:159], v[220:223], v[26:29]
	v_mfma_f32_16x16x32_bf16 v[18:21], v[164:167], v[220:223], v[18:21]
	v_mfma_f32_16x16x32_bf16 v[46:49], v[168:171], v[192:195], v[46:49]
	v_mfma_f32_16x16x32_bf16 v[38:41], v[176:179], v[192:195], v[38:41]
	v_mfma_f32_16x16x32_bf16 v[30:33], v[168:171], v[200:203], v[30:33]
	v_mfma_f32_16x16x32_bf16 v[22:25], v[176:179], v[200:203], v[22:25]
	v_mfma_f32_16x16x32_bf16 v[14:17], v[168:171], v[208:211], v[14:17]
	v_mfma_f32_16x16x32_bf16 v[10:13], v[176:179], v[208:211], v[10:13]
	v_mfma_f32_16x16x32_bf16 v[6:9], v[168:171], v[216:219], v[6:9]
	v_mfma_f32_16x16x32_bf16 v[2:5], v[176:179], v[216:219], v[2:5]
	v_mfma_f32_16x16x32_bf16 v[46:49], v[172:175], v[196:199], v[46:49]
	v_mfma_f32_16x16x32_bf16 v[38:41], v[188:191], v[196:199], v[38:41]
	v_mfma_f32_16x16x32_bf16 v[30:33], v[172:175], v[204:207], v[30:33]
	v_mfma_f32_16x16x32_bf16 v[22:25], v[188:191], v[204:207], v[22:25]
	v_mfma_f32_16x16x32_bf16 v[14:17], v[172:175], v[212:215], v[14:17]
	v_mfma_f32_16x16x32_bf16 v[10:13], v[188:191], v[212:215], v[10:13]
	v_mfma_f32_16x16x32_bf16 v[6:9], v[172:175], v[220:223], v[6:9]
	v_mfma_f32_16x16x32_bf16 v[2:5], v[188:191], v[220:223], v[2:5]
	s_barrier
	s_add_i32 s58, 0, 0x18000
	v_add_u32_e32 v155, s58, v149
	s_add_i32 s59, 0, 0x1c000
	ds_read_b128 v[142:145], v155
	ds_read_b128 v[156:159], v155 offset:1024
	ds_read_b128 v[160:163], v155 offset:2048
	ds_read_b128 v[164:167], v155 offset:3072
	v_add_u32_e32 v155, s59, v149
	ds_read_b128 v[168:171], v155
	ds_read_b128 v[172:175], v155 offset:1024
	ds_read_b128 v[176:179], v155 offset:2048
	ds_read_b128 v[188:191], v155 offset:3072
	s_add_u32 s36, s36, 0x40000
	s_addc_u32 s37, s37, 0
	s_mov_b32 m0, s41
	v_lshl_add_u64 v[228:229], s[36:37], 0, v[130:131]
	ds_read_b128 v[192:195], v154 offset:32768
	ds_read_b128 v[196:199], v154 offset:33792
	ds_read_b128 v[200:203], v154 offset:34816
	ds_read_b128 v[204:207], v154 offset:35840
	ds_read_b128 v[208:211], v154 offset:36864
	ds_read_b128 v[212:215], v154 offset:37888
	ds_read_b128 v[216:219], v154 offset:38912
	ds_read_b128 v[220:223], v154 offset:39936
	global_load_lds_dwordx4 v[228:229], off
	v_lshl_add_u64 v[228:229], s[36:37], 0, v[132:133]
	s_mov_b32 m0, s42
	s_nop 0
	global_load_lds_dwordx4 v[228:229], off
	s_waitcnt vmcnt(8)
	s_waitcnt lgkmcnt(0)
	s_barrier
	s_waitcnt lgkmcnt(0)
	v_mfma_f32_16x16x32_bf16 v[126:129], v[142:145], v[192:195], v[126:129]
	v_mfma_f32_16x16x32_bf16 v[122:125], v[160:163], v[192:195], v[122:125]
	v_mfma_f32_16x16x32_bf16 v[118:121], v[142:145], v[200:203], v[118:121]
	v_mfma_f32_16x16x32_bf16 v[114:117], v[160:163], v[200:203], v[114:117]
	v_mfma_f32_16x16x32_bf16 v[106:109], v[142:145], v[208:211], v[106:109]
	v_mfma_f32_16x16x32_bf16 v[98:101], v[160:163], v[208:211], v[98:101]
	v_mfma_f32_16x16x32_bf16 v[90:93], v[142:145], v[216:219], v[90:93]
	v_mfma_f32_16x16x32_bf16 v[82:85], v[160:163], v[216:219], v[82:85]
	v_mfma_f32_16x16x32_bf16 v[126:129], v[156:159], v[196:199], v[126:129]
	v_mfma_f32_16x16x32_bf16 v[122:125], v[164:167], v[196:199], v[122:125]
	v_mfma_f32_16x16x32_bf16 v[118:121], v[156:159], v[204:207], v[118:121]
	v_mfma_f32_16x16x32_bf16 v[114:117], v[164:167], v[204:207], v[114:117]
	v_mfma_f32_16x16x32_bf16 v[106:109], v[156:159], v[212:215], v[106:109]
	v_mfma_f32_16x16x32_bf16 v[98:101], v[164:167], v[212:215], v[98:101]
	v_mfma_f32_16x16x32_bf16 v[90:93], v[156:159], v[220:223], v[90:93]
	v_mfma_f32_16x16x32_bf16 v[82:85], v[164:167], v[220:223], v[82:85]
	v_mfma_f32_16x16x32_bf16 v[110:113], v[168:171], v[192:195], v[110:113]
	v_mfma_f32_16x16x32_bf16 v[102:105], v[176:179], v[192:195], v[102:105]
	v_mfma_f32_16x16x32_bf16 v[94:97], v[168:171], v[200:203], v[94:97]
	v_mfma_f32_16x16x32_bf16 v[86:89], v[176:179], v[200:203], v[86:89]
	v_mfma_f32_16x16x32_bf16 v[78:81], v[168:171], v[208:211], v[78:81]
	v_mfma_f32_16x16x32_bf16 v[74:77], v[176:179], v[208:211], v[74:77]
	v_mfma_f32_16x16x32_bf16 v[70:73], v[168:171], v[216:219], v[70:73]
	v_mfma_f32_16x16x32_bf16 v[66:69], v[176:179], v[216:219], v[66:69]
	v_mfma_f32_16x16x32_bf16 v[110:113], v[172:175], v[196:199], v[110:113]
	v_mfma_f32_16x16x32_bf16 v[102:105], v[188:191], v[196:199], v[102:105]
	v_mfma_f32_16x16x32_bf16 v[94:97], v[172:175], v[204:207], v[94:97]
	v_mfma_f32_16x16x32_bf16 v[86:89], v[188:191], v[204:207], v[86:89]
	v_mfma_f32_16x16x32_bf16 v[78:81], v[172:175], v[212:215], v[78:81]
	v_mfma_f32_16x16x32_bf16 v[74:77], v[188:191], v[212:215], v[74:77]
	v_mfma_f32_16x16x32_bf16 v[70:73], v[172:175], v[220:223], v[70:73]
	v_mfma_f32_16x16x32_bf16 v[66:69], v[188:191], v[220:223], v[66:69]
	s_barrier
; #define PG8_STAGE(bufoff, gbase) do { _Pragma("unroll") for (int _i = 0; _i < 2; ++_i) \
;         __builtin_amdgcn_global_load_lds((const unsigned*)((const char*)(gbase) + voff[_i]), (LAS unsigned*)(lds + (bufoff) + ldsw + _i * 8192), 16, 0, 0); } while (0)
; #define PG8_LDA(dst, b, h) do { _Pragma("unroll") for (int m = 0; m < 4; ++m) _Pragma("unroll") for (int k = 0; k < 2; ++k) dst[m][k] = *(const LAS bf16x8*)(lds + PG8_SA(b, h) + aoff + m * 2048 + k * 1024); } while (0)
; #define PG8_LDB(dst, b, h) do { _Pragma("unroll") for (int n = 0; n < 2; ++n) _Pragma("unroll") for (int k = 0; k < 2; ++k) dst[n][k] = *(const LAS bf16x8*)(lds + PG8_SB(b, h) + boff + n * 2048 + k * 1024); } while (0)
; #define PG8_MMA(ai, bj, At, Bt) do { __builtin_amdgcn_s_setprio(1); _Pragma("unroll") for (int m = 0; m < 4; ++m) _Pragma("unroll") for (int n = 0; n < 2; ++n) _Pragma("unroll") for (int k = 0; k < 2; ++k) \
;         acc[ai][bj][m][n] = __builtin_amdgcn_mfma_f32_16x16x32_bf16(Bt[n][k], At[m][k], acc[ai][bj][m][n], 0, 0, 0); __builtin_amdgcn_s_setprio(0); } while (0)
; #define PG8_WAIT_V(n) asm volatile("s_waitcnt vmcnt(" #n ")" ::: "memory")
; #define PG8_WAIT_L(n) asm volatile("s_waitcnt lgkmcnt(" #n ")" ::: "memory")
; #define PG8_BAR __builtin_amdgcn_s_barrier()
; #define PG8_SCHED __builtin_amdgcn_sched_barrier(0)
; template <int EPI> ...
;     ...
;             PG8_LDB(B0, 1, 0); PG8_LDB(B1, 1, 1); PG8_SCHED; PG8_LDA(At, 1, 0); PG8_STAGE(PG8_SA(0, 1), a2 + hstep);
;             PG8_WAIT_V(8); PG8_WAIT_L(0); PG8_BAR; PG8_MMA(0, 0, At, B0); PG8_MMA(0, 1, At, B1); PG8_BAR; PG8_SCHED;
;             PG8_LDA(At, 1, 1); PG8_STAGE(PG8_SB(1, 0), b3); PG8_STAGE(PG8_SB(1, 1), b3 + hstep); PG8_STAGE(PG8_SA(1, 0), a3);
;             PG8_WAIT_V(8); PG8_WAIT_L(0); PG8_BAR; PG8_MMA(1, 0, At, B0); PG8_MMA(1, 1, At, B1); PG8_BAR; PG8_SCHED;
;         }
	s_add_i32 s36, s58, s39
	v_lshl_add_u64 v[146:147], v[146:147], 0, s[10:11]
	s_mov_b32 m0, s36
	ds_read_b128 v[192:195], v154 offset:49152
	ds_read_b128 v[196:199], v154 offset:50176
	ds_read_b128 v[200:203], v154 offset:51200
	ds_read_b128 v[204:207], v154 offset:52224
	ds_read_b128 v[208:211], v154 offset:53248
	ds_read_b128 v[212:215], v154 offset:54272
	ds_read_b128 v[216:219], v154 offset:55296
	ds_read_b128 v[220:223], v154 offset:56320
	global_load_lds_dwordx4 v[146:147], off
	s_add_i32 m0, s36, 0x2000
	s_add_u32 s34, s34, 0x40080
	v_lshl_add_u64 v[146:147], v[180:181], 0, s[10:11]
	s_addc_u32 s35, s35, 0
	s_add_i32 s36, s59, s39
	global_load_lds_dwordx4 v[146:147], off
	v_lshl_add_u64 v[146:147], s[34:35], 0, v[130:131]
	s_mov_b32 m0, s36
	s_nop 0
	global_load_lds_dwordx4 v[146:147], off
	v_lshl_add_u64 v[146:147], s[34:35], 0, v[132:133]
	s_add_i32 m0, s36, 0x2000
	s_nop 0
	global_load_lds_dwordx4 v[146:147], off
	v_lshl_add_u64 v[146:147], v[224:225], 0, s[10:11]
	s_mov_b32 m0, s43
	s_nop 0
	global_load_lds_dwordx4 v[146:147], off
	v_lshl_add_u64 v[146:147], v[226:227], 0, s[10:11]
	s_mov_b32 m0, s44
	s_nop 0
	global_load_lds_dwordx4 v[146:147], off
	s_waitcnt vmcnt(8)
	s_waitcnt lgkmcnt(0)
	s_barrier
	s_waitcnt lgkmcnt(0)
	v_mfma_f32_16x16x32_bf16 v[62:65], v[142:145], v[192:195], v[62:65]
	v_mfma_f32_16x16x32_bf16 v[58:61], v[160:163], v[192:195], v[58:61]
	v_mfma_f32_16x16x32_bf16 v[54:57], v[142:145], v[200:203], v[54:57]
	v_mfma_f32_16x16x32_bf16 v[50:53], v[160:163], v[200:203], v[50:53]
	v_mfma_f32_16x16x32_bf16 v[42:45], v[142:145], v[208:211], v[42:45]
	v_mfma_f32_16x16x32_bf16 v[34:37], v[160:163], v[208:211], v[34:37]
	v_mfma_f32_16x16x32_bf16 v[26:29], v[142:145], v[216:219], v[26:29]
	v_mfma_f32_16x16x32_bf16 v[18:21], v[160:163], v[216:219], v[18:21]
	v_mfma_f32_16x16x32_bf16 v[62:65], v[156:159], v[196:199], v[62:65]
	v_mfma_f32_16x16x32_bf16 v[58:61], v[164:167], v[196:199], v[58:61]
	v_mfma_f32_16x16x32_bf16 v[54:57], v[156:159], v[204:207], v[54:57]
	v_mfma_f32_16x16x32_bf16 v[50:53], v[164:167], v[204:207], v[50:53]
	v_mfma_f32_16x16x32_bf16 v[42:45], v[156:159], v[212:215], v[42:45]
	v_mfma_f32_16x16x32_bf16 v[34:37], v[164:167], v[212:215], v[34:37]
	v_mfma_f32_16x16x32_bf16 v[26:29], v[156:159], v[220:223], v[26:29]
	v_mfma_f32_16x16x32_bf16 v[18:21], v[164:167], v[220:223], v[18:21]
	v_mfma_f32_16x16x32_bf16 v[46:49], v[168:171], v[192:195], v[46:49]
	v_mfma_f32_16x16x32_bf16 v[38:41], v[176:179], v[192:195], v[38:41]
	v_mfma_f32_16x16x32_bf16 v[30:33], v[168:171], v[200:203], v[30:33]
	v_mfma_f32_16x16x32_bf16 v[22:25], v[176:179], v[200:203], v[22:25]
	v_mfma_f32_16x16x32_bf16 v[14:17], v[168:171], v[208:211], v[14:17]
	v_mfma_f32_16x16x32_bf16 v[10:13], v[176:179], v[208:211], v[10:13]
	v_mfma_f32_16x16x32_bf16 v[6:9], v[168:171], v[216:219], v[6:9]
	v_mfma_f32_16x16x32_bf16 v[2:5], v[176:179], v[216:219], v[2:5]
	v_mfma_f32_16x16x32_bf16 v[46:49], v[172:175], v[196:199], v[46:49]
	v_mfma_f32_16x16x32_bf16 v[38:41], v[188:191], v[196:199], v[38:41]
	v_mfma_f32_16x16x32_bf16 v[30:33], v[172:175], v[204:207], v[30:33]
	v_mfma_f32_16x16x32_bf16 v[22:25], v[188:191], v[204:207], v[22:25]
	v_mfma_f32_16x16x32_bf16 v[14:17], v[172:175], v[212:215], v[14:17]
	v_mfma_f32_16x16x32_bf16 v[10:13], v[188:191], v[212:215], v[10:13]
	v_mfma_f32_16x16x32_bf16 v[6:9], v[172:175], v[220:223], v[6:9]
	v_mfma_f32_16x16x32_bf16 v[2:5], v[188:191], v[220:223], v[2:5]
	s_barrier
	s_add_u32 s30, s30, 0x100
	s_addc_u32 s31, s31, 0
	s_add_u32 s55, s55, 0x100
	s_addc_u32 s56, s56, 0
	s_cmp_ge_u32 s57, s52
	s_mov_b32 s34, s57
	s_cbranch_scc0 .LBB0_825
	s_and_b64 vcc, exec, s[12:13]
	s_cbranch_vccz .LBB0_830
	s_barrier
	s_cmp_lt_i32 s0, 0
	s_mov_b64 s[30:31], -1
	s_cbranch_scc1 .LBB0_831

; #define PG8_STAGE(bufoff, gbase) do { _Pragma("unroll") for (int _i = 0; _i < 2; ++_i) \
;         __builtin_amdgcn_global_load_lds((const unsigned*)((const char*)(gbase) + voff[_i]), (LAS unsigned*)(lds + (bufoff) + ldsw + _i * 8192), 16, 0, 0); } while (0)
; #define PG8_LDA(dst, b, h) do { _Pragma("unroll") for (int m = 0; m < 4; ++m) _Pragma("unroll") for (int k = 0; k < 2; ++k) dst[m][k] = *(const LAS bf16x8*)(lds + PG8_SA(b, h) + aoff + m * 2048 + k * 1024); } while (0)
; #define PG8_LDB(dst, b, h) do { _Pragma("unroll") for (int n = 0; n < 2; ++n) _Pragma("unroll") for (int k = 0; k < 2; ++k) dst[n][k] = *(const LAS bf16x8*)(lds + PG8_SB(b, h) + boff + n * 2048 + k * 1024); } while (0)
; #define PG8_MMA(ai, bj, At, Bt) do { __builtin_amdgcn_s_setprio(1); _Pragma("unroll") for (int m = 0; m < 4; ++m) _Pragma("unroll") for (int n = 0; n < 2; ++n) _Pragma("unroll") for (int k = 0; k < 2; ++k) \
;         acc[ai][bj][m][n] = __builtin_amdgcn_mfma_f32_16x16x32_bf16(Bt[n][k], At[m][k], acc[ai][bj][m][n], 0, 0, 0); __builtin_amdgcn_s_setprio(0); } while (0)
; #define PG8_WAIT_V(n) asm volatile("s_waitcnt vmcnt(" #n ")" ::: "memory")
; #define PG8_WAIT_L(n) asm volatile("s_waitcnt lgkmcnt(" #n ")" ::: "memory")
; #define PG8_BAR __builtin_amdgcn_s_barrier()
; #define PG8_SCHED __builtin_amdgcn_sched_barrier(0)
; template <int EPI> ...
;     ...
;             PG8_WAIT_V(8); PG8_WAIT_L(0); PG8_BAR; PG8_MMA(0, 0, At, B0); PG8_MMA(0, 1, At, B1); PG8_BAR; PG8_SCHED;
;             PG8_LDA(At, 0, 1); PG8_STAGE(PG8_SB(0, 0), b2); PG8_STAGE(PG8_SB(0, 1), b2 + hstep); PG8_STAGE(PG8_SA(0, 0), a2);
;             PG8_WAIT_V(8); PG8_WAIT_L(0); PG8_BAR; PG8_MMA(1, 0, At, B0); PG8_MMA(1, 1, At, B1); PG8_BAR; PG8_SCHED;
;             PG8_LDB(B0, 1, 0); PG8_LDB(B1, 1, 1); PG8_SCHED; PG8_LDA(At, 1, 0); PG8_STAGE(PG8_SA(0, 1), a2 + hstep);
.Lup_wdone_0:
	s_waitcnt lgkmcnt(0)
	s_barrier
	s_waitcnt lgkmcnt(0)
	v_mfma_f32_16x16x32_bf16 v[150:153], v[38:41], v[162:165], v[150:153]
	v_mfma_f32_16x16x32_bf16 v[158:161], v[46:49], v[162:165], v[158:161]
	v_mfma_f32_16x16x32_bf16 v[134:137], v[38:41], v[170:173], v[134:137]
	v_mfma_f32_16x16x32_bf16 v[142:145], v[46:49], v[170:173], v[142:145]
	v_mfma_f32_16x16x32_bf16 v[118:121], v[38:41], v[178:181], v[118:121]
	v_mfma_f32_16x16x32_bf16 v[126:129], v[46:49], v[178:181], v[126:129]
	v_mfma_f32_16x16x32_bf16 v[110:113], v[38:41], v[218:221], v[110:113]
	v_mfma_f32_16x16x32_bf16 v[106:109], v[46:49], v[218:221], v[106:109]
	v_mfma_f32_16x16x32_bf16 v[150:153], v[42:45], v[166:169], v[150:153]
	v_mfma_f32_16x16x32_bf16 v[158:161], v[50:53], v[166:169], v[158:161]
	v_mfma_f32_16x16x32_bf16 v[134:137], v[42:45], v[174:177], v[134:137]
	v_mfma_f32_16x16x32_bf16 v[142:145], v[50:53], v[174:177], v[142:145]
	v_mfma_f32_16x16x32_bf16 v[118:121], v[42:45], v[214:217], v[118:121]
	v_mfma_f32_16x16x32_bf16 v[126:129], v[50:53], v[214:217], v[126:129]
	v_mfma_f32_16x16x32_bf16 v[110:113], v[42:45], v[222:225], v[110:113]
	v_mfma_f32_16x16x32_bf16 v[106:109], v[50:53], v[222:225], v[106:109]
	v_mfma_f32_16x16x32_bf16 v[146:149], v[54:57], v[162:165], v[146:149]
	v_mfma_f32_16x16x32_bf16 v[154:157], v[66:69], v[162:165], v[154:157]
	v_mfma_f32_16x16x32_bf16 v[130:133], v[54:57], v[170:173], v[130:133]
	v_mfma_f32_16x16x32_bf16 v[138:141], v[66:69], v[170:173], v[138:141]
	v_mfma_f32_16x16x32_bf16 v[114:117], v[54:57], v[178:181], v[114:117]
	v_mfma_f32_16x16x32_bf16 v[122:125], v[66:69], v[178:181], v[122:125]
	v_mfma_f32_16x16x32_bf16 v[102:105], v[54:57], v[218:221], v[102:105]
	v_mfma_f32_16x16x32_bf16 v[98:101], v[66:69], v[218:221], v[98:101]
	v_mfma_f32_16x16x32_bf16 v[146:149], v[58:61], v[166:169], v[146:149]
	v_mfma_f32_16x16x32_bf16 v[154:157], v[70:73], v[166:169], v[154:157]
	v_mfma_f32_16x16x32_bf16 v[130:133], v[58:61], v[174:177], v[130:133]
	v_mfma_f32_16x16x32_bf16 v[138:141], v[70:73], v[174:177], v[138:141]
	v_mfma_f32_16x16x32_bf16 v[114:117], v[58:61], v[214:217], v[114:117]
	v_mfma_f32_16x16x32_bf16 v[122:125], v[70:73], v[214:217], v[122:125]
	v_mfma_f32_16x16x32_bf16 v[102:105], v[58:61], v[222:225], v[102:105]
	v_mfma_f32_16x16x32_bf16 v[98:101], v[70:73], v[222:225], v[98:101]
	s_barrier
	s_add_i32 s84, s75, s65
	v_lshl_add_u64 v[230:231], s[58:59], 0, v[194:195]
	s_mov_b32 m0, s84
	ds_read_b128 v[162:165], v193 offset:16384
	ds_read_b128 v[166:169], v193 offset:17408
	ds_read_b128 v[170:173], v193 offset:18432
	ds_read_b128 v[174:177], v193 offset:19456
	ds_read_b128 v[178:181], v193 offset:20480
	ds_read_b128 v[214:217], v193 offset:21504
	ds_read_b128 v[218:221], v193 offset:22528
	ds_read_b128 v[222:225], v193 offset:23552
	global_load_lds_dwordx4 v[230:231], off
	s_add_i32 m0, s84, 0x2000
	s_add_u32 s84, s58, 0x40000
	v_lshl_add_u64 v[232:233], s[58:59], 0, v[196:197]
	s_addc_u32 s85, s59, 0
	s_add_i32 s86, s76, s65
	global_load_lds_dwordx4 v[232:233], off
	v_lshl_add_u64 v[226:227], s[84:85], 0, v[194:195]
	s_mov_b32 m0, s86
	v_lshl_add_u64 v[234:235], s[60:61], 0, v[194:195]
	global_load_lds_dwordx4 v[226:227], off
	v_lshl_add_u64 v[226:227], s[84:85], 0, v[196:197]
	s_add_i32 m0, s86, 0x2000
	v_lshl_add_u64 v[236:237], s[60:61], 0, v[196:197]
	global_load_lds_dwordx4 v[226:227], off
	s_mov_b32 m0, s66
	s_nop 0
	global_load_lds_dwordx4 v[234:235], off
	s_mov_b32 m0, s67
	s_nop 0
	global_load_lds_dwordx4 v[236:237], off
	s_cmp_lg_u32 s83, -2
	s_cbranch_scc1 .Lup_strict_1
	s_cmp_lt_u32 s70, 2
	s_cbranch_scc1 .Lup_strict_1
	s_waitcnt vmcnt(24)
	s_branch .Lup_wdone_1

; #define PG8_STAGE(bufoff, gbase) do { _Pragma("unroll") for (int _i = 0; _i < 2; ++_i) \
;         __builtin_amdgcn_global_load_lds((const unsigned*)((const char*)(gbase) + voff[_i]), (LAS unsigned*)(lds + (bufoff) + ldsw + _i * 8192), 16, 0, 0); } while (0)
; #define PG8_LDA(dst, b, h) do { _Pragma("unroll") for (int m = 0; m < 4; ++m) _Pragma("unroll") for (int k = 0; k < 2; ++k) dst[m][k] = *(const LAS bf16x8*)(lds + PG8_SA(b, h) + aoff + m * 2048 + k * 1024); } while (0)
; #define PG8_LDB(dst, b, h) do { _Pragma("unroll") for (int n = 0; n < 2; ++n) _Pragma("unroll") for (int k = 0; k < 2; ++k) dst[n][k] = *(const LAS bf16x8*)(lds + PG8_SB(b, h) + boff + n * 2048 + k * 1024); } while (0)
; #define PG8_MMA(ai, bj, At, Bt) do { __builtin_amdgcn_s_setprio(1); _Pragma("unroll") for (int m = 0; m < 4; ++m) _Pragma("unroll") for (int n = 0; n < 2; ++n) _Pragma("unroll") for (int k = 0; k < 2; ++k) \
;         acc[ai][bj][m][n] = __builtin_amdgcn_mfma_f32_16x16x32_bf16(Bt[n][k], At[m][k], acc[ai][bj][m][n], 0, 0, 0); __builtin_amdgcn_s_setprio(0); } while (0)
; #define PG8_WAIT_V(n) asm volatile("s_waitcnt vmcnt(" #n ")" ::: "memory")
; #define PG8_WAIT_L(n) asm volatile("s_waitcnt lgkmcnt(" #n ")" ::: "memory")
; #define PG8_BAR __builtin_amdgcn_s_barrier()
; #define PG8_SCHED __builtin_amdgcn_sched_barrier(0)
; template <int EPI> ...
;     ...
;             PG8_WAIT_V(8); PG8_WAIT_L(0); PG8_BAR; PG8_MMA(1, 0, At, B0); PG8_MMA(1, 1, At, B1); PG8_BAR; PG8_SCHED;
;             PG8_LDB(B0, 1, 0); PG8_LDB(B1, 1, 1); PG8_SCHED; PG8_LDA(At, 1, 0); PG8_STAGE(PG8_SA(0, 1), a2 + hstep);
;             PG8_WAIT_V(8); PG8_WAIT_L(0); PG8_BAR; PG8_MMA(0, 0, At, B0); PG8_MMA(0, 1, At, B1); PG8_BAR; PG8_SCHED;
;             PG8_LDA(At, 1, 1); PG8_STAGE(PG8_SB(1, 0), b3); PG8_STAGE(PG8_SB(1, 1), b3 + hstep); PG8_STAGE(PG8_SA(1, 0), a3);
;             PG8_WAIT_V(8); PG8_WAIT_L(0); PG8_BAR; PG8_MMA(1, 0, At, B0); PG8_MMA(1, 1, At, B1); PG8_BAR; PG8_SCHED;
.Lup_wdone_1:
	s_waitcnt lgkmcnt(0)
	s_barrier
	s_waitcnt lgkmcnt(0)
	v_mfma_f32_16x16x32_bf16 v[86:89], v[38:41], v[162:165], v[86:89]
	v_mfma_f32_16x16x32_bf16 v[94:97], v[46:49], v[162:165], v[94:97]
	v_mfma_f32_16x16x32_bf16 v[62:65], v[38:41], v[170:173], v[62:65]
	v_mfma_f32_16x16x32_bf16 v[78:81], v[46:49], v[170:173], v[78:81]
	v_mfma_f32_16x16x32_bf16 v[22:25], v[38:41], v[178:181], v[22:25]
	v_mfma_f32_16x16x32_bf16 v[30:33], v[46:49], v[178:181], v[30:33]
	v_mfma_f32_16x16x32_bf16 v[14:17], v[38:41], v[218:221], v[14:17]
	v_mfma_f32_16x16x32_bf16 v[10:13], v[46:49], v[218:221], v[10:13]
	v_mfma_f32_16x16x32_bf16 v[86:89], v[42:45], v[166:169], v[86:89]
	v_mfma_f32_16x16x32_bf16 v[94:97], v[50:53], v[166:169], v[94:97]
	v_mfma_f32_16x16x32_bf16 v[62:65], v[42:45], v[174:177], v[62:65]
	v_mfma_f32_16x16x32_bf16 v[78:81], v[50:53], v[174:177], v[78:81]
	v_mfma_f32_16x16x32_bf16 v[22:25], v[42:45], v[214:217], v[22:25]
	v_mfma_f32_16x16x32_bf16 v[30:33], v[50:53], v[214:217], v[30:33]
	v_mfma_f32_16x16x32_bf16 v[14:17], v[42:45], v[222:225], v[14:17]
	v_mfma_f32_16x16x32_bf16 v[10:13], v[50:53], v[222:225], v[10:13]
	v_mfma_f32_16x16x32_bf16 v[34:37], v[54:57], v[170:173], v[34:37]
	v_mfma_f32_16x16x32_bf16 v[18:21], v[54:57], v[178:181], v[18:21]
	v_mfma_f32_16x16x32_bf16 v[26:29], v[66:69], v[178:181], v[26:29]
	v_mfma_f32_16x16x32_bf16 v[6:9], v[54:57], v[218:221], v[6:9]
	v_mfma_f32_16x16x32_bf16 v[2:5], v[66:69], v[218:221], v[2:5]
	v_mfma_f32_16x16x32_bf16 v[38:41], v[54:57], v[162:165], v[82:85]
	v_mfma_f32_16x16x32_bf16 v[42:45], v[66:69], v[162:165], v[90:93]
	v_mfma_f32_16x16x32_bf16 v[34:37], v[58:61], v[174:177], v[34:37]
	v_mfma_f32_16x16x32_bf16 v[46:49], v[66:69], v[170:173], v[74:77]
	v_mfma_f32_16x16x32_bf16 v[18:21], v[58:61], v[214:217], v[18:21]
	v_mfma_f32_16x16x32_bf16 v[26:29], v[70:73], v[214:217], v[26:29]
	v_mfma_f32_16x16x32_bf16 v[6:9], v[58:61], v[222:225], v[6:9]
	v_mfma_f32_16x16x32_bf16 v[2:5], v[70:73], v[222:225], v[2:5]
	v_mfma_f32_16x16x32_bf16 v[38:41], v[58:61], v[166:169], v[38:41]
	v_mfma_f32_16x16x32_bf16 v[42:45], v[70:73], v[166:169], v[42:45]
	v_mfma_f32_16x16x32_bf16 v[46:49], v[70:73], v[174:177], v[46:49]
	s_barrier
	s_add_i32 s84, 0, 0x18000
	s_add_i32 s85, 0, 0x1c000
	v_add_u32_e32 v66, s84, v183
	v_add_u32_e32 v74, s85, v183
	ds_read_b128 v[50:53], v66
	ds_read_b128 v[54:57], v66 offset:1024
	ds_read_b128 v[58:61], v66 offset:2048
	ds_read_b128 v[66:69], v66 offset:3072
	ds_read_b128 v[70:73], v74
	ds_read_b128 v[162:165], v74 offset:1024
	ds_read_b128 v[166:169], v74 offset:2048
	ds_read_b128 v[170:173], v74 offset:3072
	s_add_u32 s60, s60, 0x40000
	s_addc_u32 s61, s61, 0
	s_mov_b32 m0, s68
	v_lshl_add_u64 v[226:227], s[60:61], 0, v[194:195]
	ds_read_b128 v[74:77], v193 offset:32768
	ds_read_b128 v[82:85], v193 offset:33792
	ds_read_b128 v[90:93], v193 offset:34816
	ds_read_b128 v[174:177], v193 offset:35840
	ds_read_b128 v[178:181], v193 offset:36864
	ds_read_b128 v[214:217], v193 offset:37888
	ds_read_b128 v[218:221], v193 offset:38912
	ds_read_b128 v[222:225], v193 offset:39936
	global_load_lds_dwordx4 v[226:227], off
	v_lshl_add_u64 v[226:227], s[60:61], 0, v[196:197]
	s_mov_b32 m0, s69
	s_nop 0
	global_load_lds_dwordx4 v[226:227], off
	s_waitcnt vmcnt(8)
	s_waitcnt lgkmcnt(0)
	s_barrier
	s_waitcnt lgkmcnt(0)
	v_mfma_f32_16x16x32_bf16 v[150:153], v[50:53], v[74:77], v[150:153]
	v_mfma_f32_16x16x32_bf16 v[158:161], v[58:61], v[74:77], v[158:161]
	v_mfma_f32_16x16x32_bf16 v[134:137], v[50:53], v[90:93], v[134:137]
	v_mfma_f32_16x16x32_bf16 v[142:145], v[58:61], v[90:93], v[142:145]
	v_mfma_f32_16x16x32_bf16 v[118:121], v[50:53], v[178:181], v[118:121]
	v_mfma_f32_16x16x32_bf16 v[126:129], v[58:61], v[178:181], v[126:129]
	v_mfma_f32_16x16x32_bf16 v[110:113], v[50:53], v[218:221], v[110:113]
	v_mfma_f32_16x16x32_bf16 v[106:109], v[58:61], v[218:221], v[106:109]
	v_mfma_f32_16x16x32_bf16 v[150:153], v[54:57], v[82:85], v[150:153]
	v_mfma_f32_16x16x32_bf16 v[158:161], v[66:69], v[82:85], v[158:161]
	v_mfma_f32_16x16x32_bf16 v[134:137], v[54:57], v[174:177], v[134:137]
	v_mfma_f32_16x16x32_bf16 v[142:145], v[66:69], v[174:177], v[142:145]
	v_mfma_f32_16x16x32_bf16 v[118:121], v[54:57], v[214:217], v[118:121]
	v_mfma_f32_16x16x32_bf16 v[126:129], v[66:69], v[214:217], v[126:129]
	v_mfma_f32_16x16x32_bf16 v[110:113], v[54:57], v[222:225], v[110:113]
	v_mfma_f32_16x16x32_bf16 v[106:109], v[66:69], v[222:225], v[106:109]
	v_mfma_f32_16x16x32_bf16 v[146:149], v[70:73], v[74:77], v[146:149]
	v_mfma_f32_16x16x32_bf16 v[74:77], v[166:169], v[74:77], v[154:157]
	v_mfma_f32_16x16x32_bf16 v[154:157], v[170:173], v[82:85], v[74:77]
	v_mfma_f32_16x16x32_bf16 v[74:77], v[70:73], v[90:93], v[130:133]
	v_mfma_f32_16x16x32_bf16 v[130:133], v[162:165], v[174:177], v[74:77]
	v_mfma_f32_16x16x32_bf16 v[74:77], v[166:169], v[90:93], v[138:141]
	v_mfma_f32_16x16x32_bf16 v[138:141], v[170:173], v[174:177], v[74:77]
	v_mfma_f32_16x16x32_bf16 v[74:77], v[70:73], v[178:181], v[114:117]
	v_mfma_f32_16x16x32_bf16 v[114:117], v[162:165], v[214:217], v[74:77]
	v_mfma_f32_16x16x32_bf16 v[74:77], v[166:169], v[178:181], v[122:125]
	v_mfma_f32_16x16x32_bf16 v[122:125], v[170:173], v[214:217], v[74:77]
	v_mfma_f32_16x16x32_bf16 v[74:77], v[70:73], v[218:221], v[102:105]
	v_mfma_f32_16x16x32_bf16 v[102:105], v[162:165], v[222:225], v[74:77]
	v_mfma_f32_16x16x32_bf16 v[74:77], v[166:169], v[218:221], v[98:101]
	v_mfma_f32_16x16x32_bf16 v[146:149], v[162:165], v[82:85], v[146:149]
	v_mfma_f32_16x16x32_bf16 v[98:101], v[170:173], v[222:225], v[74:77]
	s_barrier
; #define PG8_STAGE(bufoff, gbase) do { _Pragma("unroll") for (int _i = 0; _i < 2; ++_i) \
;         __builtin_amdgcn_global_load_lds((const unsigned*)((const char*)(gbase) + voff[_i]), (LAS unsigned*)(lds + (bufoff) + ldsw + _i * 8192), 16, 0, 0); } while (0)
; #define PG8_LDA(dst, b, h) do { _Pragma("unroll") for (int m = 0; m < 4; ++m) _Pragma("unroll") for (int k = 0; k < 2; ++k) dst[m][k] = *(const LAS bf16x8*)(lds + PG8_SA(b, h) + aoff + m * 2048 + k * 1024); } while (0)
; #define PG8_LDB(dst, b, h) do { _Pragma("unroll") for (int n = 0; n < 2; ++n) _Pragma("unroll") for (int k = 0; k < 2; ++k) dst[n][k] = *(const LAS bf16x8*)(lds + PG8_SB(b, h) + boff + n * 2048 + k * 1024); } while (0)
; #define PG8_WAIT_V(n) asm volatile("s_waitcnt vmcnt(" #n ")" ::: "memory")
; #define PG8_WAIT_L(n) asm volatile("s_waitcnt lgkmcnt(" #n ")" ::: "memory")
; #define PG8_BAR __builtin_amdgcn_s_barrier()
; #define PG8_SCHED __builtin_amdgcn_sched_barrier(0)
; template <int EPI> ...
;     ...
;         for (int t = 0; t < cnk; t += 2) {
;             const bool last = (t == cnk - 2);
;             const char* a1 = cA + (size_t)(t + 1) * kstep;
;             const char* a2 = last ? nA : cA + (size_t)(t + 2) * kstep; const char* b2 = last ? nB : cB + (size_t)(t + 2) * kstep;
;             const char* a3 = a2 + kstep; const char* b3 = b2 + kstep;
;             PG8_LDB(B0, 0, 0); PG8_LDB(B1, 0, 1); PG8_SCHED; PG8_LDA(At, 0, 0); PG8_STAGE(PG8_SA(1, 1), a1 + hstep);
;             PG8_WAIT_V(8); PG8_WAIT_L(0); PG8_BAR; PG8_MMA(0, 0, At, B0); PG8_MMA(0, 1, At, B1); PG8_BAR; PG8_SCHED;
;             PG8_LDA(At, 0, 1); PG8_STAGE(PG8_SB(0, 0), b2); PG8_STAGE(PG8_SB(0, 1), b2 + hstep); PG8_STAGE(PG8_SA(0, 0), a2);
;             PG8_WAIT_V(8); PG8_WAIT_L(0); PG8_BAR; PG8_MMA(1, 0, At, B0); PG8_MMA(1, 1, At, B1); PG8_BAR; PG8_SCHED;
;             PG8_LDB(B0, 1, 0); PG8_LDB(B1, 1, 1); PG8_SCHED; PG8_LDA(At, 1, 0); PG8_STAGE(PG8_SA(0, 1), a2 + hstep);
;             PG8_WAIT_V(8); PG8_WAIT_L(0); PG8_BAR; PG8_MMA(0, 0, At, B0); PG8_MMA(0, 1, At, B1); PG8_BAR; PG8_SCHED;
;             PG8_LDA(At, 1, 1); PG8_STAGE(PG8_SB(1, 0), b3); PG8_STAGE(PG8_SB(1, 1), b3 + hstep); PG8_STAGE(PG8_SA(1, 0), a3);
;             PG8_WAIT_V(8); PG8_WAIT_L(0); PG8_BAR; PG8_MMA(1, 0, At, B0); PG8_MMA(1, 1, At, B1); PG8_BAR; PG8_SCHED;
;         }
;         if (wr == 0) PG8_BAR;
	s_add_i32 s60, s84, s65
	v_lshl_add_u64 v[82:83], v[230:231], 0, s[26:27]
	s_mov_b32 m0, s60
	s_nop 0
	ds_read_b128 v[74:77], v193 offset:49152
	ds_read_b128 v[90:93], v193 offset:50176
	ds_read_b128 v[174:177], v193 offset:51200
	ds_read_b128 v[178:181], v193 offset:52224
	ds_read_b128 v[214:217], v193 offset:53248
	ds_read_b128 v[218:221], v193 offset:54272
	ds_read_b128 v[222:225], v193 offset:55296
	ds_read_b128 v[226:229], v193 offset:56320
	global_load_lds_dwordx4 v[82:83], off
	s_add_i32 m0, s60, 0x2000
	s_add_u32 s58, s58, 0x40080
	v_lshl_add_u64 v[82:83], v[232:233], 0, s[26:27]
	s_addc_u32 s59, s59, 0
	s_add_i32 s60, s85, s65
	global_load_lds_dwordx4 v[82:83], off
	v_lshl_add_u64 v[82:83], s[58:59], 0, v[194:195]
	s_mov_b32 m0, s60
	s_nop 0
	global_load_lds_dwordx4 v[82:83], off
	v_lshl_add_u64 v[82:83], s[58:59], 0, v[196:197]
	s_add_i32 m0, s60, 0x2000
	s_nop 0
	global_load_lds_dwordx4 v[82:83], off
	v_lshl_add_u64 v[82:83], v[234:235], 0, s[26:27]
	s_mov_b32 m0, s72
	s_nop 0
	global_load_lds_dwordx4 v[82:83], off
	v_lshl_add_u64 v[82:83], v[236:237], 0, s[26:27]
	s_mov_b32 m0, s73
	s_nop 0
	global_load_lds_dwordx4 v[82:83], off
	s_waitcnt vmcnt(8)
	s_waitcnt lgkmcnt(0)
	s_barrier
	s_waitcnt lgkmcnt(0)
	v_mfma_f32_16x16x32_bf16 v[82:85], v[50:53], v[74:77], v[86:89]
	v_mfma_f32_16x16x32_bf16 v[86:89], v[54:57], v[90:93], v[82:85]
	v_mfma_f32_16x16x32_bf16 v[82:85], v[58:61], v[74:77], v[94:97]
	v_mfma_f32_16x16x32_bf16 v[62:65], v[50:53], v[174:177], v[62:65]
	v_mfma_f32_16x16x32_bf16 v[78:81], v[58:61], v[174:177], v[78:81]
	v_mfma_f32_16x16x32_bf16 v[22:25], v[50:53], v[214:217], v[22:25]
	v_mfma_f32_16x16x32_bf16 v[30:33], v[58:61], v[214:217], v[30:33]
	v_mfma_f32_16x16x32_bf16 v[14:17], v[50:53], v[222:225], v[14:17]
	v_mfma_f32_16x16x32_bf16 v[10:13], v[58:61], v[222:225], v[10:13]
	v_mfma_f32_16x16x32_bf16 v[94:97], v[66:69], v[90:93], v[82:85]
	v_mfma_f32_16x16x32_bf16 v[62:65], v[54:57], v[178:181], v[62:65]
	v_mfma_f32_16x16x32_bf16 v[78:81], v[66:69], v[178:181], v[78:81]
	v_mfma_f32_16x16x32_bf16 v[22:25], v[54:57], v[218:221], v[22:25]
	v_mfma_f32_16x16x32_bf16 v[30:33], v[66:69], v[218:221], v[30:33]
	v_mfma_f32_16x16x32_bf16 v[14:17], v[54:57], v[226:229], v[14:17]
	v_mfma_f32_16x16x32_bf16 v[10:13], v[66:69], v[226:229], v[10:13]
	v_mfma_f32_16x16x32_bf16 v[38:41], v[70:73], v[74:77], v[38:41]
	v_mfma_f32_16x16x32_bf16 v[82:85], v[162:165], v[90:93], v[38:41]
	v_mfma_f32_16x16x32_bf16 v[38:41], v[166:169], v[74:77], v[42:45]
	v_mfma_f32_16x16x32_bf16 v[90:93], v[170:173], v[90:93], v[38:41]
	v_mfma_f32_16x16x32_bf16 v[34:37], v[70:73], v[174:177], v[34:37]
	v_mfma_f32_16x16x32_bf16 v[38:41], v[166:169], v[174:177], v[46:49]
	v_mfma_f32_16x16x32_bf16 v[18:21], v[70:73], v[214:217], v[18:21]
	v_mfma_f32_16x16x32_bf16 v[26:29], v[166:169], v[214:217], v[26:29]
	v_mfma_f32_16x16x32_bf16 v[6:9], v[70:73], v[222:225], v[6:9]
	v_mfma_f32_16x16x32_bf16 v[2:5], v[166:169], v[222:225], v[2:5]
	v_mfma_f32_16x16x32_bf16 v[34:37], v[162:165], v[178:181], v[34:37]
	v_mfma_f32_16x16x32_bf16 v[74:77], v[170:173], v[178:181], v[38:41]
	v_mfma_f32_16x16x32_bf16 v[18:21], v[162:165], v[218:221], v[18:21]
	v_mfma_f32_16x16x32_bf16 v[26:29], v[170:173], v[218:221], v[26:29]
	v_mfma_f32_16x16x32_bf16 v[6:9], v[162:165], v[226:229], v[6:9]
	v_mfma_f32_16x16x32_bf16 v[2:5], v[170:173], v[226:229], v[2:5]
	s_barrier
	s_add_i32 s83, s83, 2
	s_add_u32 s56, s56, 0x100
	s_addc_u32 s57, s57, 0
	s_add_u32 s62, s62, 0x100
	s_addc_u32 s63, s63, 0
	s_cmp_gt_u32 s83, 13
	s_cbranch_scc0 .LBB0_970
	s_and_b64 vcc, exec, s[28:29]
	s_cbranch_vccz .LBB0_973
	s_barrier

; #define PG8_STAGE(bufoff, gbase) do { _Pragma("unroll") for (int _i = 0; _i < 2; ++_i) \
;         __builtin_amdgcn_global_load_lds((const unsigned*)((const char*)(gbase) + voff[_i]), (LAS unsigned*)(lds + (bufoff) + ldsw + _i * 8192), 16, 0, 0); } while (0)
; #define PG8_LDA(dst, b, h) do { _Pragma("unroll") for (int m = 0; m < 4; ++m) _Pragma("unroll") for (int k = 0; k < 2; ++k) dst[m][k] = *(const LAS bf16x8*)(lds + PG8_SA(b, h) + aoff + m * 2048 + k * 1024); } while (0)
; #define PG8_LDB(dst, b, h) do { _Pragma("unroll") for (int n = 0; n < 2; ++n) _Pragma("unroll") for (int k = 0; k < 2; ++k) dst[n][k] = *(const LAS bf16x8*)(lds + PG8_SB(b, h) + boff + n * 2048 + k * 1024); } while (0)
; #define PG8_MMA(ai, bj, At, Bt) do { __builtin_amdgcn_s_setprio(1); _Pragma("unroll") for (int m = 0; m < 4; ++m) _Pragma("unroll") for (int n = 0; n < 2; ++n) _Pragma("unroll") for (int k = 0; k < 2; ++k) \
;         acc[ai][bj][m][n] = __builtin_amdgcn_mfma_f32_16x16x32_bf16(Bt[n][k], At[m][k], acc[ai][bj][m][n], 0, 0, 0); __builtin_amdgcn_s_setprio(0); } while (0)
; #define PG8_WAIT_V(n) asm volatile("s_waitcnt vmcnt(" #n ")" ::: "memory")
; #define PG8_WAIT_L(n) asm volatile("s_waitcnt lgkmcnt(" #n ")" ::: "memory")
; #define PG8_BAR __builtin_amdgcn_s_barrier()
; #define PG8_SCHED __builtin_amdgcn_sched_barrier(0)
; template <int EPI> ...
;     ...
;             PG8_LDB(B0, 0, 0); PG8_LDB(B1, 0, 1); PG8_SCHED; PG8_LDA(At, 0, 0); PG8_STAGE(PG8_SA(1, 1), a1 + hstep);
;             PG8_WAIT_V(8); PG8_WAIT_L(0); PG8_BAR; PG8_MMA(0, 0, At, B0); PG8_MMA(0, 1, At, B1); PG8_BAR; PG8_SCHED;
;             PG8_LDA(At, 0, 1); PG8_STAGE(PG8_SB(0, 0), b2); PG8_STAGE(PG8_SB(0, 1), b2 + hstep); PG8_STAGE(PG8_SA(0, 0), a2);
;             PG8_WAIT_V(8); PG8_WAIT_L(0); PG8_BAR; PG8_MMA(1, 0, At, B0); PG8_MMA(1, 1, At, B1); PG8_BAR; PG8_SCHED;
;             PG8_LDB(B0, 1, 0); PG8_LDB(B1, 1, 1); PG8_SCHED; PG8_LDA(At, 1, 0); PG8_STAGE(PG8_SA(0, 1), a2 + hstep);
.LBB0_1246:
	ds_read_b128 v[128:131], v156
	ds_read_b128 v[132:135], v156 offset:1024
	ds_read_b128 v[148:151], v156 offset:2048
	ds_read_b128 v[160:163], v156 offset:3072
	ds_read_b128 v[164:167], v157
	ds_read_b128 v[168:171], v157 offset:1024
	ds_read_b128 v[172:175], v157 offset:2048
	ds_read_b128 v[176:179], v157 offset:3072
	s_add_i32 s57, s28, 2
	s_add_u32 s26, s24, 0x100
	s_addc_u32 s27, s25, 0
	s_cmp_eq_u32 s54, s28
	s_cselect_b32 s28, s18, s55
	s_cselect_b32 s31, s17, s27
	s_cselect_b32 s30, s16, s26
	s_cselect_b32 s29, s19, s56
	v_lshl_add_u64 v[180:181], s[24:25], 0, v[142:143]
	s_add_i32 m0, s38, 0xc000
	ds_read_b128 v[194:197], v158
	ds_read_b128 v[198:201], v158 offset:1024
	ds_read_b128 v[202:205], v158 offset:2048
	ds_read_b128 v[206:209], v158 offset:3072
	ds_read_b128 v[210:213], v158 offset:4096
	ds_read_b128 v[214:217], v158 offset:5120
	ds_read_b128 v[218:221], v158 offset:6144
	ds_read_b128 v[222:225], v158 offset:7168
	global_load_lds_dwordx4 v[180:181], off
	v_lshl_add_u64 v[180:181], s[24:25], 0, v[144:145]
	s_add_i32 m0, s38, 0xe000
	s_nop 0
	global_load_lds_dwordx4 v[180:181], off
	s_waitcnt vmcnt(8)
	s_waitcnt lgkmcnt(0)
	s_barrier
	s_waitcnt lgkmcnt(0)
	v_mfma_f32_16x16x32_bf16 v[124:127], v[128:131], v[194:197], v[124:127]
	v_mfma_f32_16x16x32_bf16 v[120:123], v[148:151], v[194:197], v[120:123]
	v_mfma_f32_16x16x32_bf16 v[116:119], v[128:131], v[202:205], v[116:119]
	v_mfma_f32_16x16x32_bf16 v[112:115], v[148:151], v[202:205], v[112:115]
	v_mfma_f32_16x16x32_bf16 v[104:107], v[128:131], v[210:213], v[104:107]
	v_mfma_f32_16x16x32_bf16 v[96:99], v[148:151], v[210:213], v[96:99]
	v_mfma_f32_16x16x32_bf16 v[88:91], v[128:131], v[218:221], v[88:91]
	v_mfma_f32_16x16x32_bf16 v[80:83], v[148:151], v[218:221], v[80:83]
	v_mfma_f32_16x16x32_bf16 v[124:127], v[132:135], v[198:201], v[124:127]
	v_mfma_f32_16x16x32_bf16 v[120:123], v[160:163], v[198:201], v[120:123]
	v_mfma_f32_16x16x32_bf16 v[116:119], v[132:135], v[206:209], v[116:119]
	v_mfma_f32_16x16x32_bf16 v[112:115], v[160:163], v[206:209], v[112:115]
	v_mfma_f32_16x16x32_bf16 v[104:107], v[132:135], v[214:217], v[104:107]
	v_mfma_f32_16x16x32_bf16 v[96:99], v[160:163], v[214:217], v[96:99]
	v_mfma_f32_16x16x32_bf16 v[88:91], v[132:135], v[222:225], v[88:91]
	v_mfma_f32_16x16x32_bf16 v[80:83], v[160:163], v[222:225], v[80:83]
	v_mfma_f32_16x16x32_bf16 v[108:111], v[164:167], v[194:197], v[108:111]
	v_mfma_f32_16x16x32_bf16 v[100:103], v[172:175], v[194:197], v[100:103]
	v_mfma_f32_16x16x32_bf16 v[92:95], v[164:167], v[202:205], v[92:95]
	v_mfma_f32_16x16x32_bf16 v[84:87], v[172:175], v[202:205], v[84:87]
	v_mfma_f32_16x16x32_bf16 v[76:79], v[164:167], v[210:213], v[76:79]
	v_mfma_f32_16x16x32_bf16 v[72:75], v[172:175], v[210:213], v[72:75]
	v_mfma_f32_16x16x32_bf16 v[68:71], v[164:167], v[218:221], v[68:71]
	v_mfma_f32_16x16x32_bf16 v[64:67], v[172:175], v[218:221], v[64:67]
	v_mfma_f32_16x16x32_bf16 v[108:111], v[168:171], v[198:201], v[108:111]
	v_mfma_f32_16x16x32_bf16 v[100:103], v[176:179], v[198:201], v[100:103]
	v_mfma_f32_16x16x32_bf16 v[92:95], v[168:171], v[206:209], v[92:95]
	v_mfma_f32_16x16x32_bf16 v[84:87], v[176:179], v[206:209], v[84:87]
	v_mfma_f32_16x16x32_bf16 v[76:79], v[168:171], v[214:217], v[76:79]
	v_mfma_f32_16x16x32_bf16 v[72:75], v[176:179], v[214:217], v[72:75]
	v_mfma_f32_16x16x32_bf16 v[68:71], v[168:171], v[222:225], v[68:71]
	v_mfma_f32_16x16x32_bf16 v[64:67], v[176:179], v[222:225], v[64:67]
	s_barrier
	s_add_i32 s24, s45, s37
	v_lshl_add_u64 v[180:181], s[28:29], 0, v[136:137]
	s_mov_b32 m0, s24
	ds_read_b128 v[194:197], v158 offset:16384
	ds_read_b128 v[198:201], v158 offset:17408
	ds_read_b128 v[202:205], v158 offset:18432
	ds_read_b128 v[206:209], v158 offset:19456
	ds_read_b128 v[210:213], v158 offset:20480
	ds_read_b128 v[214:217], v158 offset:21504
	ds_read_b128 v[218:221], v158 offset:22528
	ds_read_b128 v[222:225], v158 offset:23552
	global_load_lds_dwordx4 v[180:181], off
	s_add_i32 m0, s24, 0x2000
	s_add_u32 s24, s28, 0xb0000
	v_lshl_add_u64 v[186:187], s[28:29], 0, v[138:139]
	s_addc_u32 s25, s29, 0
	s_add_i32 s58, s46, s37
	global_load_lds_dwordx4 v[186:187], off
	v_lshl_add_u64 v[226:227], s[24:25], 0, v[136:137]
	s_mov_b32 m0, s58
	v_lshl_add_u64 v[228:229], s[30:31], 0, v[138:139]
	global_load_lds_dwordx4 v[226:227], off
	v_lshl_add_u64 v[226:227], s[24:25], 0, v[138:139]
	s_add_i32 m0, s58, 0x2000
	s_nop 0
	global_load_lds_dwordx4 v[226:227], off
	v_lshl_add_u64 v[226:227], s[30:31], 0, v[136:137]
	s_mov_b32 m0, s38
	s_nop 0
	global_load_lds_dwordx4 v[226:227], off
	s_mov_b32 m0, s39
	s_nop 0
	global_load_lds_dwordx4 v[228:229], off
	s_waitcnt vmcnt(8)
	s_waitcnt lgkmcnt(0)
	s_barrier
; #define PG8_STAGE(bufoff, gbase) do { _Pragma("unroll") for (int _i = 0; _i < 2; ++_i) \
;         __builtin_amdgcn_global_load_lds((const unsigned*)((const char*)(gbase) + voff[_i]), (LAS unsigned*)(lds + (bufoff) + ldsw + _i * 8192), 16, 0, 0); } while (0)
; #define PG8_LDA(dst, b, h) do { _Pragma("unroll") for (int m = 0; m < 4; ++m) _Pragma("unroll") for (int k = 0; k < 2; ++k) dst[m][k] = *(const LAS bf16x8*)(lds + PG8_SA(b, h) + aoff + m * 2048 + k * 1024); } while (0)
; #define PG8_LDB(dst, b, h) do { _Pragma("unroll") for (int n = 0; n < 2; ++n) _Pragma("unroll") for (int k = 0; k < 2; ++k) dst[n][k] = *(const LAS bf16x8*)(lds + PG8_SB(b, h) + boff + n * 2048 + k * 1024); } while (0)
; #define PG8_MMA(ai, bj, At, Bt) do { __builtin_amdgcn_s_setprio(1); _Pragma("unroll") for (int m = 0; m < 4; ++m) _Pragma("unroll") for (int n = 0; n < 2; ++n) _Pragma("unroll") for (int k = 0; k < 2; ++k) \
;         acc[ai][bj][m][n] = __builtin_amdgcn_mfma_f32_16x16x32_bf16(Bt[n][k], At[m][k], acc[ai][bj][m][n], 0, 0, 0); __builtin_amdgcn_s_setprio(0); } while (0)
; #define PG8_WAIT_V(n) asm volatile("s_waitcnt vmcnt(" #n ")" ::: "memory")
; #define PG8_WAIT_L(n) asm volatile("s_waitcnt lgkmcnt(" #n ")" ::: "memory")
; #define PG8_BAR __builtin_amdgcn_s_barrier()
; #define PG8_SCHED __builtin_amdgcn_sched_barrier(0)
; template <int EPI> ...
;     ...
;             PG8_WAIT_V(8); PG8_WAIT_L(0); PG8_BAR; PG8_MMA(1, 0, At, B0); PG8_MMA(1, 1, At, B1); PG8_BAR; PG8_SCHED;
;             PG8_LDB(B0, 1, 0); PG8_LDB(B1, 1, 1); PG8_SCHED; PG8_LDA(At, 1, 0); PG8_STAGE(PG8_SA(0, 1), a2 + hstep);
;             PG8_WAIT_V(8); PG8_WAIT_L(0); PG8_BAR; PG8_MMA(0, 0, At, B0); PG8_MMA(0, 1, At, B1); PG8_BAR; PG8_SCHED;
	s_waitcnt lgkmcnt(0)
	v_mfma_f32_16x16x32_bf16 v[60:63], v[128:131], v[194:197], v[60:63]
	v_mfma_f32_16x16x32_bf16 v[56:59], v[148:151], v[194:197], v[56:59]
	v_mfma_f32_16x16x32_bf16 v[52:55], v[128:131], v[202:205], v[52:55]
	v_mfma_f32_16x16x32_bf16 v[48:51], v[148:151], v[202:205], v[48:51]
	v_mfma_f32_16x16x32_bf16 v[40:43], v[128:131], v[210:213], v[40:43]
	v_mfma_f32_16x16x32_bf16 v[32:35], v[148:151], v[210:213], v[32:35]
	v_mfma_f32_16x16x32_bf16 v[24:27], v[128:131], v[218:221], v[24:27]
	v_mfma_f32_16x16x32_bf16 v[16:19], v[148:151], v[218:221], v[16:19]
	v_mfma_f32_16x16x32_bf16 v[60:63], v[132:135], v[198:201], v[60:63]
	v_mfma_f32_16x16x32_bf16 v[56:59], v[160:163], v[198:201], v[56:59]
	v_mfma_f32_16x16x32_bf16 v[52:55], v[132:135], v[206:209], v[52:55]
	v_mfma_f32_16x16x32_bf16 v[48:51], v[160:163], v[206:209], v[48:51]
	v_mfma_f32_16x16x32_bf16 v[40:43], v[132:135], v[214:217], v[40:43]
	v_mfma_f32_16x16x32_bf16 v[32:35], v[160:163], v[214:217], v[32:35]
	v_mfma_f32_16x16x32_bf16 v[24:27], v[132:135], v[222:225], v[24:27]
	v_mfma_f32_16x16x32_bf16 v[16:19], v[160:163], v[222:225], v[16:19]
	v_mfma_f32_16x16x32_bf16 v[44:47], v[164:167], v[194:197], v[44:47]
	v_mfma_f32_16x16x32_bf16 v[36:39], v[172:175], v[194:197], v[36:39]
	v_mfma_f32_16x16x32_bf16 v[28:31], v[164:167], v[202:205], v[28:31]
	v_mfma_f32_16x16x32_bf16 v[20:23], v[172:175], v[202:205], v[20:23]
	v_mfma_f32_16x16x32_bf16 v[12:15], v[164:167], v[210:213], v[12:15]
	v_mfma_f32_16x16x32_bf16 v[8:11], v[172:175], v[210:213], v[8:11]
	v_mfma_f32_16x16x32_bf16 v[4:7], v[164:167], v[218:221], v[4:7]
	v_mfma_f32_16x16x32_bf16 v[0:3], v[172:175], v[218:221], v[0:3]
	v_mfma_f32_16x16x32_bf16 v[44:47], v[168:171], v[198:201], v[44:47]
	v_mfma_f32_16x16x32_bf16 v[36:39], v[176:179], v[198:201], v[36:39]
	v_mfma_f32_16x16x32_bf16 v[28:31], v[168:171], v[206:209], v[28:31]
	v_mfma_f32_16x16x32_bf16 v[20:23], v[176:179], v[206:209], v[20:23]
	v_mfma_f32_16x16x32_bf16 v[12:15], v[168:171], v[214:217], v[12:15]
	v_mfma_f32_16x16x32_bf16 v[8:11], v[176:179], v[214:217], v[8:11]
	v_mfma_f32_16x16x32_bf16 v[4:7], v[168:171], v[222:225], v[4:7]
	v_mfma_f32_16x16x32_bf16 v[0:3], v[176:179], v[222:225], v[0:3]
	s_barrier
	s_add_i32 s58, 0, 0x18000
	v_add_u32_e32 v159, s58, v153
	s_add_i32 s59, 0, 0x1c000
	ds_read_b128 v[128:131], v159
	ds_read_b128 v[132:135], v159 offset:1024
	ds_read_b128 v[148:151], v159 offset:2048
	ds_read_b128 v[160:163], v159 offset:3072
	v_add_u32_e32 v159, s59, v153
	ds_read_b128 v[164:167], v159
	ds_read_b128 v[168:171], v159 offset:1024
	ds_read_b128 v[172:175], v159 offset:2048
	ds_read_b128 v[176:179], v159 offset:3072
	s_add_u32 s24, s30, 0xb0000
	s_addc_u32 s25, s31, 0
	s_mov_b32 m0, s40
	v_lshl_add_u64 v[230:231], s[24:25], 0, v[136:137]
	ds_read_b128 v[194:197], v158 offset:32768
	ds_read_b128 v[198:201], v158 offset:33792
	ds_read_b128 v[202:205], v158 offset:34816
	ds_read_b128 v[206:209], v158 offset:35840
	ds_read_b128 v[210:213], v158 offset:36864
	ds_read_b128 v[214:217], v158 offset:37888
	ds_read_b128 v[218:221], v158 offset:38912
	ds_read_b128 v[222:225], v158 offset:39936
	global_load_lds_dwordx4 v[230:231], off
	v_lshl_add_u64 v[230:231], s[24:25], 0, v[138:139]
	s_mov_b32 m0, s41
	s_nop 0
	global_load_lds_dwordx4 v[230:231], off
	s_waitcnt vmcnt(8)
	s_waitcnt lgkmcnt(0)
	s_barrier
	s_waitcnt lgkmcnt(0)
	v_mfma_f32_16x16x32_bf16 v[124:127], v[128:131], v[194:197], v[124:127]
	v_mfma_f32_16x16x32_bf16 v[120:123], v[148:151], v[194:197], v[120:123]
	v_mfma_f32_16x16x32_bf16 v[116:119], v[128:131], v[202:205], v[116:119]
	v_mfma_f32_16x16x32_bf16 v[112:115], v[148:151], v[202:205], v[112:115]
	v_mfma_f32_16x16x32_bf16 v[104:107], v[128:131], v[210:213], v[104:107]
	v_mfma_f32_16x16x32_bf16 v[96:99], v[148:151], v[210:213], v[96:99]
	v_mfma_f32_16x16x32_bf16 v[88:91], v[128:131], v[218:221], v[88:91]
	v_mfma_f32_16x16x32_bf16 v[80:83], v[148:151], v[218:221], v[80:83]
	v_mfma_f32_16x16x32_bf16 v[124:127], v[132:135], v[198:201], v[124:127]
	v_mfma_f32_16x16x32_bf16 v[120:123], v[160:163], v[198:201], v[120:123]
	v_mfma_f32_16x16x32_bf16 v[116:119], v[132:135], v[206:209], v[116:119]
	v_mfma_f32_16x16x32_bf16 v[112:115], v[160:163], v[206:209], v[112:115]
	v_mfma_f32_16x16x32_bf16 v[104:107], v[132:135], v[214:217], v[104:107]
	v_mfma_f32_16x16x32_bf16 v[96:99], v[160:163], v[214:217], v[96:99]
	v_mfma_f32_16x16x32_bf16 v[88:91], v[132:135], v[222:225], v[88:91]
	v_mfma_f32_16x16x32_bf16 v[80:83], v[160:163], v[222:225], v[80:83]
	v_mfma_f32_16x16x32_bf16 v[108:111], v[164:167], v[194:197], v[108:111]
	v_mfma_f32_16x16x32_bf16 v[100:103], v[172:175], v[194:197], v[100:103]
	v_mfma_f32_16x16x32_bf16 v[92:95], v[164:167], v[202:205], v[92:95]
	v_mfma_f32_16x16x32_bf16 v[84:87], v[172:175], v[202:205], v[84:87]
	v_mfma_f32_16x16x32_bf16 v[76:79], v[164:167], v[210:213], v[76:79]
	v_mfma_f32_16x16x32_bf16 v[72:75], v[172:175], v[210:213], v[72:75]
	v_mfma_f32_16x16x32_bf16 v[68:71], v[164:167], v[218:221], v[68:71]
	v_mfma_f32_16x16x32_bf16 v[64:67], v[172:175], v[218:221], v[64:67]
	v_mfma_f32_16x16x32_bf16 v[108:111], v[168:171], v[198:201], v[108:111]
	v_mfma_f32_16x16x32_bf16 v[100:103], v[176:179], v[198:201], v[100:103]
	v_mfma_f32_16x16x32_bf16 v[92:95], v[168:171], v[206:209], v[92:95]
	v_mfma_f32_16x16x32_bf16 v[84:87], v[176:179], v[206:209], v[84:87]
	v_mfma_f32_16x16x32_bf16 v[76:79], v[168:171], v[214:217], v[76:79]
	v_mfma_f32_16x16x32_bf16 v[72:75], v[176:179], v[214:217], v[72:75]
	v_mfma_f32_16x16x32_bf16 v[68:71], v[168:171], v[222:225], v[68:71]
	v_mfma_f32_16x16x32_bf16 v[64:67], v[176:179], v[222:225], v[64:67]
	s_barrier
; #define PG8_STAGE(bufoff, gbase) do { _Pragma("unroll") for (int _i = 0; _i < 2; ++_i) \
;         __builtin_amdgcn_global_load_lds((const unsigned*)((const char*)(gbase) + voff[_i]), (LAS unsigned*)(lds + (bufoff) + ldsw + _i * 8192), 16, 0, 0); } while (0)
; #define PG8_LDA(dst, b, h) do { _Pragma("unroll") for (int m = 0; m < 4; ++m) _Pragma("unroll") for (int k = 0; k < 2; ++k) dst[m][k] = *(const LAS bf16x8*)(lds + PG8_SA(b, h) + aoff + m * 2048 + k * 1024); } while (0)
; #define PG8_MMA(ai, bj, At, Bt) do { __builtin_amdgcn_s_setprio(1); _Pragma("unroll") for (int m = 0; m < 4; ++m) _Pragma("unroll") for (int n = 0; n < 2; ++n) _Pragma("unroll") for (int k = 0; k < 2; ++k) \
;         acc[ai][bj][m][n] = __builtin_amdgcn_mfma_f32_16x16x32_bf16(Bt[n][k], At[m][k], acc[ai][bj][m][n], 0, 0, 0); __builtin_amdgcn_s_setprio(0); } while (0)
; #define PG8_WAIT_V(n) asm volatile("s_waitcnt vmcnt(" #n ")" ::: "memory")
; #define PG8_WAIT_L(n) asm volatile("s_waitcnt lgkmcnt(" #n ")" ::: "memory")
; #define PG8_BAR __builtin_amdgcn_s_barrier()
; #define PG8_SCHED __builtin_amdgcn_sched_barrier(0)
; template <int EPI> ...
;     ...
;             PG8_LDA(At, 1, 1); PG8_STAGE(PG8_SB(1, 0), b3); PG8_STAGE(PG8_SB(1, 1), b3 + hstep); PG8_STAGE(PG8_SA(1, 0), a3);
;             PG8_WAIT_V(8); PG8_WAIT_L(0); PG8_BAR; PG8_MMA(1, 0, At, B0); PG8_MMA(1, 1, At, B1); PG8_BAR; PG8_SCHED;
;         }
;         if (wr == 0) PG8_BAR;
;         if (SPLIT && cur_slice >= 0) {
	s_add_i32 s24, s58, s37
	v_lshl_add_u64 v[180:181], v[180:181], 0, s[10:11]
	s_mov_b32 m0, s24
	ds_read_b128 v[194:197], v158 offset:49152
	ds_read_b128 v[198:201], v158 offset:50176
	ds_read_b128 v[202:205], v158 offset:51200
	ds_read_b128 v[206:209], v158 offset:52224
	ds_read_b128 v[210:213], v158 offset:53248
	ds_read_b128 v[214:217], v158 offset:54272
	ds_read_b128 v[218:221], v158 offset:55296
	ds_read_b128 v[222:225], v158 offset:56320
	global_load_lds_dwordx4 v[180:181], off
	s_add_i32 m0, s24, 0x2000
	s_add_u32 s24, s28, 0xb0080
	v_lshl_add_u64 v[180:181], v[186:187], 0, s[10:11]
	s_addc_u32 s25, s29, 0
	s_add_i32 s28, s59, s37
	global_load_lds_dwordx4 v[180:181], off
	v_lshl_add_u64 v[180:181], s[24:25], 0, v[136:137]
	s_mov_b32 m0, s28
	s_nop 0
	global_load_lds_dwordx4 v[180:181], off
	v_lshl_add_u64 v[180:181], s[24:25], 0, v[138:139]
	s_add_i32 m0, s28, 0x2000
	s_nop 0
	global_load_lds_dwordx4 v[180:181], off
	v_lshl_add_u64 v[180:181], v[226:227], 0, s[10:11]
	s_mov_b32 m0, s42
	s_nop 0
	global_load_lds_dwordx4 v[180:181], off
	v_lshl_add_u64 v[180:181], v[228:229], 0, s[10:11]
	s_mov_b32 m0, s43
	s_nop 0
	global_load_lds_dwordx4 v[180:181], off
	s_waitcnt vmcnt(8)
	s_waitcnt lgkmcnt(0)
	s_barrier
	s_waitcnt lgkmcnt(0)
	v_mfma_f32_16x16x32_bf16 v[60:63], v[128:131], v[194:197], v[60:63]
	v_mfma_f32_16x16x32_bf16 v[56:59], v[148:151], v[194:197], v[56:59]
	v_mfma_f32_16x16x32_bf16 v[52:55], v[128:131], v[202:205], v[52:55]
	v_mfma_f32_16x16x32_bf16 v[48:51], v[148:151], v[202:205], v[48:51]
	v_mfma_f32_16x16x32_bf16 v[40:43], v[128:131], v[210:213], v[40:43]
	v_mfma_f32_16x16x32_bf16 v[32:35], v[148:151], v[210:213], v[32:35]
	v_mfma_f32_16x16x32_bf16 v[24:27], v[128:131], v[218:221], v[24:27]
	v_mfma_f32_16x16x32_bf16 v[16:19], v[148:151], v[218:221], v[16:19]
	v_mfma_f32_16x16x32_bf16 v[60:63], v[132:135], v[198:201], v[60:63]
	v_mfma_f32_16x16x32_bf16 v[56:59], v[160:163], v[198:201], v[56:59]
	v_mfma_f32_16x16x32_bf16 v[52:55], v[132:135], v[206:209], v[52:55]
	v_mfma_f32_16x16x32_bf16 v[48:51], v[160:163], v[206:209], v[48:51]
	v_mfma_f32_16x16x32_bf16 v[40:43], v[132:135], v[214:217], v[40:43]
	v_mfma_f32_16x16x32_bf16 v[32:35], v[160:163], v[214:217], v[32:35]
	v_mfma_f32_16x16x32_bf16 v[24:27], v[132:135], v[222:225], v[24:27]
	v_mfma_f32_16x16x32_bf16 v[16:19], v[160:163], v[222:225], v[16:19]
	v_mfma_f32_16x16x32_bf16 v[44:47], v[164:167], v[194:197], v[44:47]
	v_mfma_f32_16x16x32_bf16 v[36:39], v[172:175], v[194:197], v[36:39]
	v_mfma_f32_16x16x32_bf16 v[28:31], v[164:167], v[202:205], v[28:31]
	v_mfma_f32_16x16x32_bf16 v[20:23], v[172:175], v[202:205], v[20:23]
	v_mfma_f32_16x16x32_bf16 v[12:15], v[164:167], v[210:213], v[12:15]
	v_mfma_f32_16x16x32_bf16 v[8:11], v[172:175], v[210:213], v[8:11]
	v_mfma_f32_16x16x32_bf16 v[4:7], v[164:167], v[218:221], v[4:7]
	v_mfma_f32_16x16x32_bf16 v[0:3], v[172:175], v[218:221], v[0:3]
	v_mfma_f32_16x16x32_bf16 v[44:47], v[168:171], v[198:201], v[44:47]
	v_mfma_f32_16x16x32_bf16 v[36:39], v[176:179], v[198:201], v[36:39]
	v_mfma_f32_16x16x32_bf16 v[28:31], v[168:171], v[206:209], v[28:31]
	v_mfma_f32_16x16x32_bf16 v[20:23], v[176:179], v[206:209], v[20:23]
	v_mfma_f32_16x16x32_bf16 v[12:15], v[168:171], v[214:217], v[12:15]
	v_mfma_f32_16x16x32_bf16 v[8:11], v[176:179], v[214:217], v[8:11]
	v_mfma_f32_16x16x32_bf16 v[4:7], v[168:171], v[222:225], v[4:7]
	v_mfma_f32_16x16x32_bf16 v[0:3], v[176:179], v[222:225], v[0:3]
	s_barrier
	s_add_u32 s55, s55, 0x100
	s_addc_u32 s56, s56, 0
	s_cmp_ge_u32 s57, s53
	s_mov_b64 s[24:25], s[26:27]
	s_mov_b32 s28, s57
	s_cbranch_scc0 .LBB0_1246
	s_and_b64 vcc, exec, s[12:13]
	s_cbranch_vccz .LBB0_1251
	s_barrier
	s_cmp_lt_i32 s2, 0
	s_mov_b64 s[24:25], -1
	s_cbranch_scc1 .LBB0_1252
